# scan cores: HG S3 + TOT prefix + KT/VT re-layout + ret/mamba S3 LDS reads hoisted (counted waits); mask fast path when chunk is full
# speedup vs baseline: 1.0451x; 1.0162x over previous
; #define RT_DECODE(u, b_, h_, vs_, ck_, smp_, row0_, len_) do { if ((u) < np) { b_ = cb >> 5; h_ = (cb >> 3) & 3; vs_ = cb & 7; ck_ = (u); smp_ = false; row0_ = b_ * TP + 64 * ck_; len_ = ck_ < 32 ? 64 : 16; } \
;         else { const int it_ = (cb % 256) + ((u) - np) * G; b_ = it_ >> 5; h_ = (it_ >> 3) & 3; vs_ = it_ & 7; ck_ = 0; smp_ = true; row0_ = RP + 8 * b_; len_ = 8; } } while (0)
; __device__ __forceinline__ void ret_block(ArgsP a_, unsigned char* smem) { const ArgsP a = a_;
;     ...
;     for (int uu = 0; uu < ntot_; ++uu) { const int u = uu < np ? uu : np + (uu - np) % nsmp; const int un_ = uu + 1 < np ? uu + 1 : np + (uu + 1 - np) % nsmp;
;         int b, h, vs, ck, row0, len; bool sample; RT_DECODE(u, b, h, vs, ck, sample, row0, len);
.LBB0_242:
	s_waitcnt vmcnt(0)
	s_cmp_eq_u32 s89, 64
	s_cbranch_scc1 .Lret_mask_full
	v_cmp_gt_i32_e32 vcc, s89, v133
	s_nop 1
	v_cndmask_b32_e32 v3, 0, v3, vcc
	v_cndmask_b32_e32 v2, 0, v2, vcc
	v_cndmask_b32_e32 v1, 0, v1, vcc
	v_cndmask_b32_e32 v0, 0, v0, vcc
	v_cndmask_b32_e32 v7, 0, v7, vcc
	v_cndmask_b32_e32 v6, 0, v6, vcc
	v_cndmask_b32_e32 v5, 0, v5, vcc
	v_cndmask_b32_e32 v4, 0, v4, vcc
	v_cmp_gt_i32_e32 vcc, s89, v103
	s_nop 1
	v_cndmask_b32_e32 v11, 0, v11, vcc
	v_cndmask_b32_e32 v10, 0, v10, vcc
	v_cndmask_b32_e32 v9, 0, v9, vcc
	v_cndmask_b32_e32 v8, 0, v8, vcc
	v_cndmask_b32_e32 v15, 0, v15, vcc
	v_cndmask_b32_e32 v14, 0, v14, vcc
	v_cndmask_b32_e32 v13, 0, v13, vcc
	v_cndmask_b32_e32 v12, 0, v12, vcc
	v_cmp_gt_i32_e32 vcc, s89, v105
	s_nop 1
	v_cndmask_b32_e32 v23, 0, v213, vcc
	v_cndmask_b32_e32 v22, 0, v212, vcc
	v_cndmask_b32_e32 v21, 0, v211, vcc
	v_cndmask_b32_e32 v20, 0, v210, vcc
	v_cndmask_b32_e32 v27, 0, v27, vcc
	v_cndmask_b32_e32 v26, 0, v26, vcc
	v_cndmask_b32_e32 v25, 0, v25, vcc
	v_cndmask_b32_e32 v24, 0, v24, vcc
	v_cmp_gt_i32_e32 vcc, s89, v107
	s_nop 1
	v_cndmask_b32_e32 v31, 0, v31, vcc
	v_cndmask_b32_e32 v30, 0, v30, vcc
	v_cndmask_b32_e32 v29, 0, v29, vcc
	v_cndmask_b32_e32 v28, 0, v28, vcc
	v_cndmask_b32_e32 v35, 0, v35, vcc
	v_cndmask_b32_e32 v34, 0, v34, vcc
	v_cndmask_b32_e32 v33, 0, v33, vcc
	v_cndmask_b32_e32 v32, 0, v32, vcc
	v_cmp_gt_i32_e32 vcc, s89, v117
	v_lshlrev_b32_e32 v18, 16, v203
	s_nop 0
	v_cndmask_b32_e32 v16, 0, v202, vcc
	v_cmp_gt_i32_e32 vcc, s89, v109
	s_nop 1
	v_cndmask_b32_e32 v18, 0, v18, vcc
	s_nop 0
	v_or_b32_e32 v36, v18, v16
	v_cmp_gt_i32_e32 vcc, s89, v134
	v_lshlrev_b32_e32 v18, 16, v205
	s_nop 0
	v_cndmask_b32_e32 v16, 0, v204, vcc
	v_cmp_gt_i32_e32 vcc, s89, v135
	s_nop 1
	v_cndmask_b32_e32 v18, 0, v18, vcc
	s_nop 0
	v_or_b32_e32 v37, v18, v16
	v_cmp_gt_i32_e32 vcc, s89, v136
	v_lshlrev_b32_e32 v18, 16, v207
	s_nop 0
	v_cndmask_b32_e32 v16, 0, v206, vcc
	v_cmp_gt_i32_e32 vcc, s89, v137
	s_nop 1
	v_cndmask_b32_e32 v18, 0, v18, vcc
	s_nop 0
	v_or_b32_e32 v38, v18, v16
	v_cmp_gt_i32_e32 vcc, s89, v138
	v_lshlrev_b32_e32 v18, 16, v209
	s_nop 0
	v_cndmask_b32_e32 v16, 0, v208, vcc
	v_cmp_gt_i32_e32 vcc, s89, v139
	s_nop 1
	v_cndmask_b32_e32 v18, 0, v18, vcc
	s_nop 0
	v_or_b32_e32 v39, v18, v16
	s_branch .Lret_mask_done
.Lret_mask_full:
	v_mov_b32_e32 v20, v210
	v_mov_b32_e32 v21, v211
	v_mov_b32_e32 v22, v212
	v_mov_b32_e32 v23, v213
	v_lshl_or_b32 v36, v203, 16, v202
	v_lshl_or_b32 v37, v205, 16, v204
	v_lshl_or_b32 v38, v207, 16, v206
	v_lshl_or_b32 v39, v209, 16, v208

; __device__ __forceinline__ unsigned cvt_pk_bf16(float lo, float hi) { unsigned r; asm("v_cvt_pk_bf16_f32 %0, %1, %2" : "=v"(r) : "v"(lo), "v"(hi)); return r; }
; __device__ __forceinline__ void ret_block(ArgsP a_, unsigned char* smem) { const ArgsP a = a_;
;     ...
;         { const int cp = tid & 127, jq = tid >> 7;
;           float dj[16];
; #pragma unroll
;           for (int q4 = 0; q4 < 4; ++q4) { const f32x4 t = *(const f32x4*)(DECJ + 16 * jq + 4 * q4); dj[4 * q4] = t[0]; dj[4 * q4 + 1] = t[1]; dj[4 * q4 + 2] = t[2]; dj[4 * q4 + 3] = t[3]; }
;           unsigned lo[8], hi[8];
; #pragma unroll
;           for (int e = 0; e < 8; ++e) { const int j = 16 * jq + 2 * e; const unsigned w0 = *(const unsigned*)(KB + j * LQ + 2 * cp), w1 = *(const unsigned*)(KB + (j + 1) * LQ + 2 * cp);
;               lo[e] = cvt_pk_bf16(__uint_as_float(w0 << 16) * dj[2 * e], __uint_as_float(w1 << 16) * dj[2 * e + 1]);
;               hi[e] = cvt_pk_bf16(__uint_as_float(w0 & 0xffff0000u) * dj[2 * e], __uint_as_float(w1 & 0xffff0000u) * dj[2 * e + 1]); }
;           *(u32x4*)(KT + (2 * cp) * LJ + 16 * jq) = (u32x4){lo[0], lo[1], lo[2], lo[3]}; *(u32x4*)(KT + (2 * cp) * LJ + 16 * jq + 8) = (u32x4){lo[4], lo[5], lo[6], lo[7]};
;           *(u32x4*)(KT + (2 * cp + 1) * LJ + 16 * jq) = (u32x4){hi[0], hi[1], hi[2], hi[3]}; *(u32x4*)(KT + (2 * cp + 1) * LJ + 16 * jq + 8) = (u32x4){hi[4], hi[5], hi[6], hi[7]}; }
.LBB0_269:
	ds_read_b128 v[214:217], v142
	ds_read_b128 v[218:221], v142 offset:16
	ds_read_b128 v[222:225], v142 offset:32
	ds_read_b128 v[226:229], v142 offset:48
	ds_read_b32 v230, v140 offset:33792
	ds_read_b32 v231, v141 offset:34320
	ds_read_b32 v232, v140 offset:34848
	ds_read_b32 v233, v141 offset:35376
	ds_read_b32 v234, v140 offset:35904
	ds_read_b32 v235, v141 offset:36432
	ds_read_b32 v236, v140 offset:36960
	ds_read_b32 v237, v141 offset:37488
	ds_read_b32 v238, v140 offset:38016
	ds_read_b32 v239, v141 offset:38544
	ds_read_b32 v240, v140 offset:39072
	s_waitcnt lgkmcnt(10)
	v_lshlrev_b32_e32 v19, 16, v230
	ds_read_b32 v241, v141 offset:39600
	ds_read_b32 v242, v140 offset:40128
	ds_read_b32 v243, v141 offset:40656
	ds_read_b32 v244, v140 offset:41184
	ds_read_b32 v245, v141 offset:41712
	s_waitcnt lgkmcnt(14)
	v_lshlrev_b32_e32 v80, 16, v231
	v_and_b32_e32 v16, 0xffff0000, v230
	v_and_b32_e32 v18, 0xffff0000, v231
	v_mul_f32_e32 v16, v214, v16
	v_mul_f32_e32 v18, v215, v18
	v_mul_f32_e32 v19, v214, v19
	v_cvt_pk_bf16_f32 v72, v16, v18
	v_mul_f32_e32 v80, v215, v80
	v_cvt_pk_bf16_f32 v80, v19, v80
	s_waitcnt lgkmcnt(13)
	v_lshlrev_b32_e32 v19, 16, v232
	s_waitcnt lgkmcnt(12)
	v_lshlrev_b32_e32 v73, 16, v233
	v_and_b32_e32 v16, 0xffff0000, v232
	v_and_b32_e32 v18, 0xffff0000, v233
	v_mul_f32_e32 v73, v217, v73
	v_mul_f32_e32 v16, v216, v16
	v_mul_f32_e32 v18, v217, v18
	v_mul_f32_e32 v19, v216, v19
	v_cvt_pk_bf16_f32 v81, v19, v73
	v_cvt_pk_bf16_f32 v73, v16, v18
	s_waitcnt lgkmcnt(11)
	v_lshlrev_b32_e32 v19, 16, v234
	s_waitcnt lgkmcnt(10)
	v_lshlrev_b32_e32 v74, 16, v235
	v_and_b32_e32 v16, 0xffff0000, v234
	v_and_b32_e32 v18, 0xffff0000, v235
	v_mul_f32_e32 v74, v219, v74
	v_mul_f32_e32 v16, v218, v16
	v_mul_f32_e32 v18, v219, v18
	v_mul_f32_e32 v19, v218, v19
	v_cvt_pk_bf16_f32 v82, v19, v74
	v_cvt_pk_bf16_f32 v74, v16, v18
	s_waitcnt lgkmcnt(9)
	v_lshlrev_b32_e32 v19, 16, v236
	s_waitcnt lgkmcnt(8)
	v_lshlrev_b32_e32 v75, 16, v237
	v_and_b32_e32 v16, 0xffff0000, v236
	v_and_b32_e32 v18, 0xffff0000, v237
	v_mul_f32_e32 v75, v221, v75
	v_mul_f32_e32 v16, v220, v16
	v_mul_f32_e32 v18, v221, v18
	v_mul_f32_e32 v19, v220, v19
	v_cvt_pk_bf16_f32 v83, v19, v75
	v_cvt_pk_bf16_f32 v75, v16, v18
	s_waitcnt lgkmcnt(7)
	v_lshlrev_b32_e32 v19, 16, v238
	s_waitcnt lgkmcnt(6)
	v_lshlrev_b32_e32 v88, 16, v239
	v_and_b32_e32 v16, 0xffff0000, v238
	v_and_b32_e32 v18, 0xffff0000, v239
	v_mul_f32_e32 v16, v222, v16
	v_mul_f32_e32 v18, v223, v18
	v_mul_f32_e32 v19, v222, v19
	v_cvt_pk_bf16_f32 v84, v16, v18
	v_mul_f32_e32 v88, v223, v88
	v_cvt_pk_bf16_f32 v88, v19, v88
	s_waitcnt lgkmcnt(5)
	v_lshlrev_b32_e32 v19, 16, v240
	s_waitcnt lgkmcnt(4)
	v_lshlrev_b32_e32 v85, 16, v241
	v_and_b32_e32 v16, 0xffff0000, v240
	v_and_b32_e32 v18, 0xffff0000, v241
	v_mul_f32_e32 v85, v225, v85
	v_mul_f32_e32 v16, v224, v16
	v_mul_f32_e32 v18, v225, v18
	v_mul_f32_e32 v19, v224, v19
	v_cvt_pk_bf16_f32 v89, v19, v85
	v_cvt_pk_bf16_f32 v85, v16, v18
	s_waitcnt lgkmcnt(3)
	v_lshlrev_b32_e32 v19, 16, v242
	s_waitcnt lgkmcnt(2)
	v_lshlrev_b32_e32 v86, 16, v243
	v_and_b32_e32 v16, 0xffff0000, v242
	v_and_b32_e32 v18, 0xffff0000, v243
	v_mul_f32_e32 v86, v227, v86
	v_mul_f32_e32 v16, v226, v16
	v_mul_f32_e32 v18, v227, v18
	v_mul_f32_e32 v19, v226, v19
	v_cvt_pk_bf16_f32 v90, v19, v86
	v_cvt_pk_bf16_f32 v86, v16, v18
	v_cvt_pk_bf16_f32 v77, v54, v55
	s_waitcnt lgkmcnt(1)
	v_lshlrev_b32_e32 v19, 16, v244
	s_waitcnt lgkmcnt(0)
	v_lshlrev_b32_e32 v76, 16, v245
	v_and_b32_e32 v16, 0xffff0000, v244
	v_and_b32_e32 v18, 0xffff0000, v245
	v_mul_f32_e32 v19, v228, v19
	v_mul_f32_e32 v16, v228, v16
	v_mul_f32_e32 v18, v229, v18
	v_mul_f32_e32 v76, v229, v76
	v_cvt_pk_bf16_f32 v91, v19, v76
	v_cvt_pk_bf16_f32 v87, v16, v18
	v_cvt_pk_bf16_f32 v18, v40, v41
	v_cvt_pk_bf16_f32 v19, v42, v43
	v_add_u32_e32 v16, 0x2000, v143
	ds_write_b128 v124, v[80:83]
	ds_write_b128 v124, v[88:91] offset:16
	ds_write_b128 v124, v[72:75] offset:144
	ds_write_b128 v124, v[84:87] offset:160
	v_cvt_pk_bf16_f32 v72, v44, v45
	v_cvt_pk_bf16_f32 v73, v46, v47
	v_cvt_pk_bf16_f32 v78, v56, v57
	v_cvt_pk_bf16_f32 v79, v58, v59
	ds_write2_b64 v143, v[18:19], v[78:79] offset1:4
	v_cvt_pk_bf16_f32 v18, v60, v61
	v_cvt_pk_bf16_f32 v19, v62, v63
	ds_write2_b64 v16, v[72:73], v[18:19] offset0:32 offset1:36
	v_add_u32_e32 v16, 0x4000, v143
	v_cvt_pk_bf16_f32 v74, v48, v49
	v_cvt_pk_bf16_f32 v75, v50, v51
	v_cvt_pk_bf16_f32 v18, v64, v65
	v_cvt_pk_bf16_f32 v19, v66, v67
	ds_write2_b64 v16, v[74:75], v[18:19] offset0:64 offset1:68
	v_add_u32_e32 v16, 0x6000, v143
	v_cvt_pk_bf16_f32 v76, v52, v53
	v_cvt_pk_bf16_f32 v18, v68, v69
	v_cvt_pk_bf16_f32 v19, v70, v71
	ds_write2_b64 v16, v[76:77], v[18:19] offset0:96 offset1:100
	s_waitcnt lgkmcnt(0)
	s_barrier
; __device__ __forceinline__ unsigned cvt_pk_bf16(float lo, float hi) { unsigned r; asm("v_cvt_pk_bf16_f32 %0, %1, %2" : "=v"(r) : "v"(lo), "v"(hi)); return r; }
; template <int DK, int DV, bool SEPQ> ...
;     ...
;     {
;         const float gi_i = GI[16 * m + fr];
;         const int n0 = 2 * hw, n1 = 2 * hw + 1; const bool do0 = n0 <= m, do1 = n1 <= m;
;         f32x4 acc0 = {0.f, 0.f, 0.f, 0.f}, acc1 = {0.f, 0.f, 0.f, 0.f};
; #pragma unroll
;         for (int vt = 0; vt < NVTW; ++vt) O[vt] = (f32x4){0.f, 0.f, 0.f, 0.f};
; #pragma unroll
;         for (int ks = 0; ks < DK / 32; ++ks) {
;             const bf16x8 qf = *(const bf16x8*)(QA + (16 * m + fr) * LQ + 32 * ks + 8 * fq);
;             if (do0) { const bf16x8 kf = *(const bf16x8*)(KB + (16 * n0 + fr) * LQ + 32 * ks + 8 * fq); acc0 = __builtin_amdgcn_mfma_f32_16x16x32_bf16(kf, qf, acc0, 0, 0, 0); }
;             if (do1) { const bf16x8 kf = *(const bf16x8*)(KB + (16 * n1 + fr) * LQ + 32 * ks + 8 * fq); acc1 = __builtin_amdgcn_mfma_f32_16x16x32_bf16(kf, qf, acc1, 0, 0, 0); }
;             bf16x8 qs = qf; if (SEPQ) qs = *(const bf16x8*)(QS + (16 * m + fr) * LQ + 32 * ks + 8 * fq);
; #pragma unroll
;             for (int vt = 0; vt < NVTW; ++vt) { const bf16x8 sf = *(const bf16x8*)(ST + (16 * (hw * NVTW + vt) + fr) * LQ + 32 * ks + 8 * fq); O[vt] = __builtin_amdgcn_mfma_f32_16x16x32_bf16(sf, qs, O[vt], 0, 0, 0); }
;         }
; #pragma unroll
;         for (int nn = 0; nn < 2; ++nn) {
;             const int n = 2 * hw + nn; const f32x4 acc = nn == 0 ? acc0 : acc1;
;             const f32x4 gj = *(const f32x4*)(GI + 16 * n + 4 * fq); const int i = 16 * m + fr, j0 = 16 * n + 4 * fq; float p[4];
; #pragma unroll
;             for (int e = 0; e < 4; ++e) p[e] = (j0 + e <= i) ? acc[e] * __expf(gi_i - gj[e]) : 0.f;
;             u32x2 w; w.x = cvt_pk_bf16(p[0], p[1]); w.y = cvt_pk_bf16(p[2], p[3]); *(u32x2*)(P + (16 * m + fr) * LJ + j0) = w;
;         }
;         const float ei = __expf(gi_i);
; #pragma unroll
;         for (int vt = 0; vt < NVTW; ++vt) O[vt] = O[vt] * ei;
;     }
	ds_read_b32 v92, v125
	ds_read_b128 v[214:217], v126
	ds_read_b128 v[218:221], v127 offset:33792
	ds_read_b128 v[222:225], v127 offset:42240
	ds_read_b128 v[226:229], v165
	ds_read_b128 v[230:233], v165 offset:8448
	ds_read_b128 v[166:169], v126 offset:64
	ds_read_b128 v[170:173], v127 offset:33856
	ds_read_b128 v[174:177], v127 offset:42304
	ds_read_b128 v[178:181], v165 offset:64
	ds_read_b128 v[182:185], v165 offset:8512
	s_waitcnt lgkmcnt(5)
	v_mfma_f32_16x16x32_bf16 v[76:79], v[218:221], v[214:217], 0
	v_mfma_f32_16x16x32_bf16 v[72:75], v[222:225], v[214:217], 0
	v_mfma_f32_16x16x32_bf16 v[80:83], v[226:229], v[214:217], 0
	v_mfma_f32_16x16x32_bf16 v[84:87], v[230:233], v[214:217], 0
	ds_read_b128 v[214:217], v126 offset:128
	ds_read_b128 v[218:221], v127 offset:33920
	ds_read_b128 v[222:225], v127 offset:42368
	ds_read_b128 v[226:229], v165 offset:128
	ds_read_b128 v[230:233], v165 offset:8576
	s_waitcnt lgkmcnt(5)
	v_mfma_f32_16x16x32_bf16 v[76:79], v[170:173], v[166:169], v[76:79]
	v_mfma_f32_16x16x32_bf16 v[72:75], v[174:177], v[166:169], v[72:75]
	v_mfma_f32_16x16x32_bf16 v[80:83], v[178:181], v[166:169], v[80:83]
	v_mfma_f32_16x16x32_bf16 v[84:87], v[182:185], v[166:169], v[84:87]
	ds_read_b128 v[166:169], v126 offset:192
	ds_read_b128 v[170:173], v127 offset:33984
	ds_read_b128 v[174:177], v127 offset:42432
	ds_read_b128 v[178:181], v165 offset:192
	ds_read_b128 v[182:185], v165 offset:8640
	s_waitcnt lgkmcnt(5)
	v_mfma_f32_16x16x32_bf16 v[76:79], v[218:221], v[214:217], v[76:79]
	v_mfma_f32_16x16x32_bf16 v[72:75], v[222:225], v[214:217], v[72:75]
	v_mfma_f32_16x16x32_bf16 v[80:83], v[226:229], v[214:217], v[80:83]
	v_mfma_f32_16x16x32_bf16 v[84:87], v[230:233], v[214:217], v[84:87]
	ds_read_b128 v[214:217], v126 offset:256
	ds_read_b128 v[218:221], v127 offset:34048
	ds_read_b128 v[222:225], v127 offset:42496
	ds_read_b128 v[226:229], v165 offset:256
	ds_read_b128 v[230:233], v165 offset:8704
	s_waitcnt lgkmcnt(5)
	v_mfma_f32_16x16x32_bf16 v[76:79], v[170:173], v[166:169], v[76:79]
	v_mfma_f32_16x16x32_bf16 v[72:75], v[174:177], v[166:169], v[72:75]
	v_mfma_f32_16x16x32_bf16 v[80:83], v[178:181], v[166:169], v[80:83]
	v_mfma_f32_16x16x32_bf16 v[84:87], v[182:185], v[166:169], v[84:87]
	ds_read_b128 v[166:169], v126 offset:320
	ds_read_b128 v[170:173], v127 offset:34112
	ds_read_b128 v[174:177], v127 offset:42560
	ds_read_b128 v[178:181], v165 offset:320
	ds_read_b128 v[182:185], v165 offset:8768
	s_waitcnt lgkmcnt(5)
	v_mfma_f32_16x16x32_bf16 v[76:79], v[218:221], v[214:217], v[76:79]
	v_mfma_f32_16x16x32_bf16 v[72:75], v[222:225], v[214:217], v[72:75]
	v_mfma_f32_16x16x32_bf16 v[80:83], v[226:229], v[214:217], v[80:83]
	v_mfma_f32_16x16x32_bf16 v[84:87], v[230:233], v[214:217], v[84:87]
	ds_read_b128 v[214:217], v126 offset:384
	ds_read_b128 v[218:221], v127 offset:34176
	ds_read_b128 v[222:225], v127 offset:42624
	ds_read_b128 v[226:229], v165 offset:384
	ds_read_b128 v[230:233], v165 offset:8832
	s_waitcnt lgkmcnt(5)
	v_mfma_f32_16x16x32_bf16 v[76:79], v[170:173], v[166:169], v[76:79]
	v_mfma_f32_16x16x32_bf16 v[72:75], v[174:177], v[166:169], v[72:75]
	v_mfma_f32_16x16x32_bf16 v[80:83], v[178:181], v[166:169], v[80:83]
	v_mfma_f32_16x16x32_bf16 v[84:87], v[182:185], v[166:169], v[84:87]
	ds_read_b128 v[166:169], v126 offset:448
	ds_read_b128 v[170:173], v127 offset:34240
	ds_read_b128 v[174:177], v127 offset:42688
	ds_read_b128 v[178:181], v165 offset:448
	ds_read_b128 v[182:185], v165 offset:8896
	s_waitcnt lgkmcnt(5)
	v_mfma_f32_16x16x32_bf16 v[76:79], v[218:221], v[214:217], v[76:79]
	v_mfma_f32_16x16x32_bf16 v[72:75], v[222:225], v[214:217], v[72:75]
	v_mfma_f32_16x16x32_bf16 v[80:83], v[226:229], v[214:217], v[80:83]
	v_mfma_f32_16x16x32_bf16 v[84:87], v[230:233], v[214:217], v[84:87]
	s_waitcnt lgkmcnt(0)
	v_mfma_f32_16x16x32_bf16 v[76:79], v[170:173], v[166:169], v[76:79]
	v_mfma_f32_16x16x32_bf16 v[72:75], v[174:177], v[166:169], v[72:75]
	v_mfma_f32_16x16x32_bf16 v[80:83], v[178:181], v[166:169], v[80:83]
	v_mfma_f32_16x16x32_bf16 v[84:87], v[182:185], v[166:169], v[84:87]
	s_nop 7
	v_cmp_gt_i32_e32 vcc, s89, v132
	ds_read_b128 v[88:91], v128
	s_waitcnt lgkmcnt(0)
	v_sub_f32_e32 v16, v92, v88
	v_mul_f32_e32 v16, 0x3fb8aa3b, v16
	v_exp_f32_e32 v16, v16
	v_sub_f32_e32 v18, v92, v89
	v_sub_f32_e32 v19, v92, v90
	v_mul_f32_e32 v18, 0x3fb8aa3b, v18
	v_mul_f32_e32 v16, v76, v16
	v_mul_f32_e32 v19, 0x3fb8aa3b, v19
	v_sub_f32_e32 v76, v92, v91
	v_exp_f32_e32 v18, v18
	v_exp_f32_e32 v19, v19
	v_mul_f32_e32 v76, 0x3fb8aa3b, v76
	v_exp_f32_e32 v76, v76
	v_mul_f32_e32 v18, v77, v18
	v_mul_f32_e32 v19, v78, v19
	v_cndmask_b32_e64 v18, 0, v18, s[50:51]
	v_cndmask_b32_e64 v19, v19, 0, s[52:53]
	v_mul_f32_e32 v76, v79, v76
	v_cndmask_b32_e64 v16, v16, 0, s[48:49]
	v_cndmask_b32_e64 v76, v76, 0, s[54:55]
	v_cvt_pk_bf16_f32 v18, v16, v18
	v_cvt_pk_bf16_f32 v19, v19, v76
	ds_write_b64 v129, v[18:19]
	ds_read_b128 v[76:79], v128 offset:64
	s_waitcnt lgkmcnt(0)
	v_sub_f32_e32 v16, v92, v76
	v_mul_f32_e32 v16, 0x3fb8aa3b, v16
	v_sub_f32_e32 v18, v92, v77
	v_exp_f32_e32 v16, v16
	v_mul_f32_e32 v18, 0x3fb8aa3b, v18
	v_exp_f32_e32 v18, v18
	v_sub_f32_e32 v19, v92, v78
	v_mul_f32_e32 v16, v72, v16
	v_sub_f32_e32 v72, v92, v79
	v_mul_f32_e32 v18, v73, v18
	v_mul_f32_e32 v19, 0x3fb8aa3b, v19
	v_mul_f32_e32 v72, 0x3fb8aa3b, v72
	v_cndmask_b32_e64 v16, v16, 0, s[56:57]
	v_cndmask_b32_e64 v18, 0, v18, s[58:59]
	v_exp_f32_e32 v19, v19
	v_exp_f32_e32 v72, v72
	v_cvt_pk_bf16_f32 v18, v16, v18
	v_mul_f32_e32 v16, 0x3fb8aa3b, v92
	v_exp_f32_e32 v16, v16
	v_mul_f32_e32 v19, v74, v19
	v_mul_f32_e32 v72, v75, v72
	v_cndmask_b32_e64 v19, v19, 0, s[60:61]
	v_cndmask_b32_e64 v72, v72, 0, s[62:63]
	v_cvt_pk_bf16_f32 v19, v19, v72
	ds_write_b64 v129, v[18:19] offset:32
	v_pk_mul_f32 v[72:73], v[16:17], v[80:81] op_sel_hi:[0,1]
	v_pk_mul_f32 v[74:75], v[16:17], v[82:83] op_sel_hi:[0,1]
	v_pk_mul_f32 v[76:77], v[16:17], v[84:85] op_sel_hi:[0,1]
	v_pk_mul_f32 v[78:79], v[16:17], v[86:87] op_sel_hi:[0,1]
	s_waitcnt lgkmcnt(0)
	s_barrier
; template <int DK, int DV, bool SEPQ> ...
;     ...
;     __syncthreads();
; #pragma unroll
;     for (int ks = 0; ks < 2; ++ks) { const bf16x8 pf = *(const bf16x8*)(P + (16 * m + fr) * LJ + 32 * ks + 8 * fq);
; #pragma unroll
;         for (int vt = 0; vt < NVTW; ++vt) { const bf16x8 vf = *(const bf16x8*)(VT + (16 * (hw * NVTW + vt) + fr) * LJ + 32 * ks + 8 * fq); O[vt] = __builtin_amdgcn_mfma_f32_16x16x32_bf16(vf, pf, O[vt], 0, 0, 0); } }
; #pragma unroll
;     for (int ct = 0; ct < NCTW; ++ct) { const int ctg = wid * NCTW + ct; const f32x4 dec = *(const f32x4*)(SDEC + 16 * ctg + 4 * fq);
; #pragma unroll
;         for (int vt = 0; vt < NVT; ++vt) S[ct][vt] = S[ct][vt] * dec;
; #pragma unroll
;         for (int ks = 0; ks < 2; ++ks) { const bf16x8 kf = *(const bf16x8*)(KT + (16 * ctg + fr) * LJ + 32 * ks + 8 * fq);
; #pragma unroll
;             for (int vt = 0; vt < NVT; ++vt) { const bf16x8 vf = *(const bf16x8*)(VT2 + (16 * vt + fr) * LJ + 32 * ks + 8 * fq); S[ct][vt] = __builtin_amdgcn_mfma_f32_16x16x32_bf16(kf, vf, S[ct][vt], 0, 0, 0); } } }
	ds_read_b128 v[214:217], v130
	ds_read_b128 v[218:221], v144
	ds_read_b128 v[222:225], v144 offset:2304
	ds_read_b128 v[226:229], v130 offset:64
	ds_read_b128 v[230:233], v144 offset:64
	ds_read_b128 v[234:237], v144 offset:2368
	ds_read_b128 v[238:241], v131
	ds_read_b128 v[242:245], v145
	ds_read_b128 v[246:249], v147
	ds_read_b128 v[166:169], v147 offset:2304
	ds_read_b128 v[170:173], v147 offset:4608
	ds_read_b128 v[174:177], v147 offset:6912
	ds_read_b128 v[178:181], v145 offset:64
	ds_read_b128 v[182:185], v147 offset:64
	ds_read_b128 v[80:83], v147 offset:2368
	s_waitcnt lgkmcnt(13)
	v_mfma_f32_16x16x32_bf16 v[72:75], v[218:221], v[214:217], v[72:75]
	ds_read_b128 v[84:87], v147 offset:4672
	ds_read_b128 v[88:91], v147 offset:6976
	s_waitcnt lgkmcnt(14)
	v_mfma_f32_16x16x32_bf16 v[76:79], v[222:225], v[214:217], v[76:79]
	ds_read_b128 v[218:221], v131 offset:64
	s_waitcnt lgkmcnt(13)
	v_mfma_f32_16x16x32_bf16 v[72:75], v[230:233], v[226:229], v[72:75]
	ds_read_b128 v[214:217], v164
	ds_read_b128 v[222:225], v164 offset:64
	s_waitcnt lgkmcnt(14)
	v_mfma_f32_16x16x32_bf16 v[76:79], v[234:237], v[226:229], v[76:79]
	s_waitcnt lgkmcnt(13)
	v_pk_mul_f32 v[42:43], v[42:43], v[240:241]
	v_pk_mul_f32 v[40:41], v[40:41], v[238:239]
	v_pk_mul_f32 v[46:47], v[46:47], v[240:241]
	v_pk_mul_f32 v[44:45], v[44:45], v[238:239]
	v_pk_mul_f32 v[50:51], v[50:51], v[240:241]
	v_pk_mul_f32 v[48:49], v[48:49], v[238:239]
	v_pk_mul_f32 v[54:55], v[54:55], v[240:241]
	v_pk_mul_f32 v[52:53], v[52:53], v[238:239]
	s_waitcnt lgkmcnt(11)
	v_mfma_f32_16x16x32_bf16 v[40:43], v[242:245], v[246:249], v[40:43]
	s_waitcnt lgkmcnt(10)
	v_mfma_f32_16x16x32_bf16 v[44:47], v[242:245], v[166:169], v[44:47]
	s_waitcnt lgkmcnt(9)
	v_mfma_f32_16x16x32_bf16 v[48:51], v[242:245], v[170:173], v[48:51]
	s_waitcnt lgkmcnt(8)
	v_mfma_f32_16x16x32_bf16 v[52:55], v[242:245], v[174:177], v[52:55]
	s_waitcnt lgkmcnt(6)
	v_mfma_f32_16x16x32_bf16 v[40:43], v[178:181], v[182:185], v[40:43]
	s_waitcnt lgkmcnt(5)
	v_mfma_f32_16x16x32_bf16 v[44:47], v[178:181], v[80:83], v[44:47]
	s_waitcnt lgkmcnt(4)
	v_mfma_f32_16x16x32_bf16 v[48:51], v[178:181], v[84:87], v[48:51]
	s_waitcnt lgkmcnt(3)
	v_mfma_f32_16x16x32_bf16 v[52:55], v[178:181], v[88:91], v[52:55]
	s_waitcnt lgkmcnt(2)
	v_pk_mul_f32 v[58:59], v[58:59], v[220:221]
	v_pk_mul_f32 v[56:57], v[56:57], v[218:219]
	v_pk_mul_f32 v[62:63], v[62:63], v[220:221]
	v_pk_mul_f32 v[60:61], v[60:61], v[218:219]
	v_pk_mul_f32 v[66:67], v[66:67], v[220:221]
	v_pk_mul_f32 v[64:65], v[64:65], v[218:219]
	v_pk_mul_f32 v[70:71], v[70:71], v[220:221]
	v_pk_mul_f32 v[68:69], v[68:69], v[218:219]
	s_waitcnt lgkmcnt(1)
	v_mfma_f32_16x16x32_bf16 v[56:59], v[214:217], v[246:249], v[56:59]
	v_mfma_f32_16x16x32_bf16 v[60:63], v[214:217], v[166:169], v[60:63]
	v_mfma_f32_16x16x32_bf16 v[64:67], v[214:217], v[170:173], v[64:67]
	v_mfma_f32_16x16x32_bf16 v[68:71], v[214:217], v[174:177], v[68:71]
	s_waitcnt lgkmcnt(0)
	v_mfma_f32_16x16x32_bf16 v[56:59], v[222:225], v[182:185], v[56:59]
	v_mfma_f32_16x16x32_bf16 v[60:63], v[222:225], v[80:83], v[60:63]
	v_mfma_f32_16x16x32_bf16 v[64:67], v[222:225], v[84:87], v[64:67]
	v_mfma_f32_16x16x32_bf16 v[68:71], v[222:225], v[88:91], v[68:71]
	s_and_saveexec_b64 s[64:65], vcc
	s_cbranch_execz .LBB0_303
	v_add_u32_e32 v18, s88, v132
	v_ashrrev_i32_e32 v19, 31, v18
	v_lshlrev_b64 v[18:19], 12, v[18:19]
	v_lshl_add_u64 v[18:19], s[26:27], 0, v[18:19]
	s_lshl_b32 s70, s91, 10
	s_mov_b32 s71, s12
	v_lshl_add_u64 v[18:19], v[18:19], 0, s[70:71]
	s_lshl_b32 s70, s90, 7
	v_lshl_add_u64 v[18:19], v[18:19], 0, s[70:71]
	v_mov_b32_e32 v113, v17
	v_lshl_add_u64 v[18:19], v[18:19], 0, v[112:113]
	v_mov_b32_e32 v115, v17
	v_cvt_pk_bf16_f32 v72, v72, v73
	v_cvt_pk_bf16_f32 v73, v74, v75
	v_lshl_add_u64 v[18:19], v[18:19], 0, v[114:115]
	global_store_dwordx2 v[18:19], v[72:73], off
	v_cvt_pk_bf16_f32 v72, v76, v77
	v_cvt_pk_bf16_f32 v73, v78, v79
	global_store_dwordx2 v[18:19], v[72:73], off offset:32

; #define MB_DECODE(u, b_, hd_, ck_, smp_, row0_, len_) do { if ((u) < np) { b_ = cb >> 5; hd_ = cb & 31; ck_ = (u); smp_ = false; row0_ = b_ * TP + 64 * ck_; len_ = ck_ < 32 ? 64 : 16; } \
;         else { const int it_ = (cb % 256) + ((u) - np) * G; b_ = it_ >> 5; hd_ = it_ & 31; ck_ = 0; smp_ = true; row0_ = RP + 8 * b_; len_ = 8; } } while (0)
; __device__ __forceinline__ void mamba_block(ArgsP a_, unsigned char* smem) { const ArgsP a = a_;
;     ...
;     for (int uu = 0; uu < ntot_; ++uu) { const int u = uu < np ? uu : np + (uu - np) % nsmp; const int un_ = uu + 1 < np ? uu + 1 : np + (uu + 1 - np) % nsmp;
;         int b, hd, ck, row0, len; bool sample; MB_DECODE(u, b, hd, ck, sample, row0, len);
.LBB0_333:
	s_waitcnt vmcnt(0)
	s_cmp_eq_u32 s73, 64
	s_cbranch_scc1 .Lmb_mask_done
	v_cmp_gt_i32_e32 vcc, s73, v85
	s_nop 1
	v_cndmask_b32_e32 v3, 0, v3, vcc
	v_cndmask_b32_e32 v2, 0, v2, vcc
	v_cndmask_b32_e32 v1, 0, v1, vcc
	v_cndmask_b32_e32 v0, 0, v0, vcc
	v_cndmask_b32_e32 v7, 0, v7, vcc
	v_cndmask_b32_e32 v6, 0, v6, vcc
	v_cndmask_b32_e32 v5, 0, v5, vcc
	v_cndmask_b32_e32 v4, 0, v4, vcc
	v_cmp_gt_i32_e32 vcc, s73, v73
	s_nop 1
	v_cndmask_b32_e32 v11, 0, v11, vcc
	v_cndmask_b32_e32 v10, 0, v10, vcc
	v_cndmask_b32_e32 v9, 0, v9, vcc
	v_cndmask_b32_e32 v8, 0, v8, vcc
	v_cndmask_b32_e32 v15, 0, v15, vcc
	v_cndmask_b32_e32 v14, 0, v14, vcc
	v_cndmask_b32_e32 v13, 0, v13, vcc
	v_cndmask_b32_e32 v12, 0, v12, vcc
	v_cmp_gt_i32_e32 vcc, s73, v78
	s_nop 1
	v_cndmask_b32_e32 v115, 0, v115, vcc
	v_cmp_gt_i32_e32 vcc, s73, v86
	s_nop 1
	v_cndmask_b32_e32 v116, 0, v116, vcc
	v_cmp_gt_i32_e32 vcc, s73, v88
	s_nop 1
	v_cndmask_b32_e32 v117, 0, v117, vcc
	v_cmp_gt_i32_e32 vcc, s73, v90
	s_nop 1
	v_cndmask_b32_e32 v120, 0, v120, vcc
	v_cmp_gt_i32_e32 vcc, s73, v92
	s_nop 1
	v_cndmask_b32_e32 v118, 0, v118, vcc
	v_cmp_gt_i32_e32 vcc, s73, v94
	s_nop 1
	v_cndmask_b32_e32 v119, 0, v119, vcc
	v_cmp_gt_i32_e32 vcc, s73, v96
	s_nop 1
	v_cndmask_b32_e32 v121, 0, v121, vcc
	v_cmp_gt_i32_e32 vcc, s73, v98
	s_nop 1
	v_cndmask_b32_e32 v122, 0, v122, vcc

; __device__ __forceinline__ unsigned cvt_pk_bf16(float lo, float hi) { unsigned r; asm("v_cvt_pk_bf16_f32 %0, %1, %2" : "=v"(r) : "v"(lo), "v"(hi)); return r; }
; __device__ __forceinline__ float bf2f(bf16_t b) { return __uint_as_float(((unsigned)b) << 16); }
; __device__ __forceinline__ void mamba_block(ArgsP a_, unsigned char* smem) { const ArgsP a = a_;
;     ...
;         { unsigned w1[4], w2[4];
; #pragma unroll
;           for (int e = 0; e < 4; ++e) { const int j = 8 * jg + 2 * e; const float x0 = bf2f(xpre[2 * e]), x1 = bf2f(xpre[2 * e + 1]);
;               w1[e] = cvt_pk_bf16(x0 * DTV[j], x1 * DTV[j + 1]); w2[e] = cvt_pk_bf16(x0 * W2[j], x1 * W2[j + 1]); }
;           *(u32x4*)(VT + vv * LJ + 8 * jg) = (u32x4){w1[0], w1[1], w1[2], w1[3]}; *(u32x4*)(VT2 + vv * LJ + 8 * jg) = (u32x4){w2[0], w2[1], w2[2], w2[3]}; }
;         { const int cp = tid & 63, jq = tid >> 6;
;           unsigned lo[4], hi[4];
; #pragma unroll
;           for (int e = 0; e < 4; ++e) { const int j = 8 * jq + 2 * e; const unsigned w0 = *(const unsigned*)(KB + j * LQ + 2 * cp), w1 = *(const unsigned*)(KB + (j + 1) * LQ + 2 * cp);
;               lo[e] = (w0 & 0xffffu) | (w1 << 16); hi[e] = (w0 >> 16) | (w1 & 0xffff0000u); }
;           *(u32x4*)(KT + (2 * cp) * LJ + 8 * jq) = (u32x4){lo[0], lo[1], lo[2], lo[3]}; *(u32x4*)(KT + (2 * cp + 1) * LJ + 8 * jq) = (u32x4){hi[0], hi[1], hi[2], hi[3]}; }
.LBB0_348:
	s_or_b64 exec, exec, s[74:75]
	s_waitcnt vmcnt(0) lgkmcnt(0)
	s_barrier
	ds_read_b64 v[220:221], v75
	ds_read_b64 v[222:223], v87
	ds_read_b64 v[224:225], v89
	ds_read_b64 v[226:227], v91
	ds_read_b64 v[228:229], v93
	ds_read_b64 v[230:231], v95
	ds_read_b64 v[232:233], v97
	ds_read_b64 v[234:235], v99
	v_lshlrev_b32_e32 v16, 16, v115
	v_lshlrev_b32_e32 v37, 16, v116
	v_lshlrev_b32_e32 v38, 16, v120
	v_lshlrev_b32_e32 v39, 16, v119
	s_waitcnt lgkmcnt(7)
	v_mul_f32_e32 v18, v220, v16
	v_mul_f32_e32 v19, v221, v37
	v_cvt_pk_bf16_f32 v36, v18, v19
	v_lshlrev_b32_e32 v43, 16, v122
	s_mov_b32 s22, 0xffff0000
	s_cmp_ge_i32 s69, s63
	s_waitcnt lgkmcnt(6)
	v_mul_f32_e32 v16, v222, v16
	v_mul_f32_e32 v18, v223, v37
	v_cvt_pk_bf16_f32 v40, v16, v18
	v_lshlrev_b32_e32 v16, 16, v117
	s_waitcnt lgkmcnt(5)
	v_mul_f32_e32 v18, v224, v16
	v_mul_f32_e32 v19, v225, v38
	v_cvt_pk_bf16_f32 v37, v18, v19
	s_waitcnt lgkmcnt(4)
	v_mul_f32_e32 v16, v226, v16
	v_mul_f32_e32 v18, v227, v38
	v_cvt_pk_bf16_f32 v41, v16, v18
	v_lshlrev_b32_e32 v16, 16, v118
	s_waitcnt lgkmcnt(3)
	v_mul_f32_e32 v18, v228, v16
	v_mul_f32_e32 v19, v229, v39
	v_cvt_pk_bf16_f32 v38, v18, v19
	s_waitcnt lgkmcnt(2)
	v_mul_f32_e32 v16, v230, v16
	v_mul_f32_e32 v18, v231, v39
	v_cvt_pk_bf16_f32 v42, v16, v18
	v_lshlrev_b32_e32 v16, 16, v121
	s_waitcnt lgkmcnt(1)
	v_mul_f32_e32 v18, v232, v16
	v_mul_f32_e32 v19, v233, v43
	v_cvt_pk_bf16_f32 v39, v18, v19
	s_waitcnt lgkmcnt(0)
	v_mul_f32_e32 v16, v234, v16
	v_mul_f32_e32 v18, v235, v43
	v_cvt_pk_bf16_f32 v43, v16, v18
	ds_write_b128 v79, v[36:39] offset:53248
	ds_write_b128 v79, v[40:43] offset:62464
	ds_read_b32 v236, v100 offset:17408
	ds_read_b32 v237, v101 offset:17680
	ds_read_b32 v238, v102 offset:17408
	ds_read_b32 v239, v103 offset:17680
	ds_read_b32 v240, v104 offset:17408
	ds_read_b32 v241, v105 offset:17680
	ds_read_b32 v242, v106 offset:17408
	ds_read_b32 v243, v107 offset:17680
	s_waitcnt lgkmcnt(7)
	v_and_b32_e32 v19, 0xffff, v236
	v_lshrrev_b32_e32 v16, 16, v236
	s_waitcnt lgkmcnt(6)
	v_lshl_or_b32 v36, v237, 16, v19
	v_and_or_b32 v40, v237, s22, v16
	s_waitcnt lgkmcnt(5)
	v_and_b32_e32 v19, 0xffff, v238
	v_lshrrev_b32_e32 v16, 16, v238
	s_waitcnt lgkmcnt(4)
	v_lshl_or_b32 v37, v239, 16, v19
	v_and_or_b32 v41, v239, s22, v16
	s_waitcnt lgkmcnt(3)
	v_and_b32_e32 v19, 0xffff, v240
	v_lshrrev_b32_e32 v16, 16, v240
	s_waitcnt lgkmcnt(2)
	v_lshl_or_b32 v38, v241, 16, v19
	v_and_or_b32 v42, v241, s22, v16
	s_waitcnt lgkmcnt(1)
	v_and_b32_e32 v19, 0xffff, v242
	s_waitcnt lgkmcnt(0)
	v_lshl_or_b32 v39, v243, 16, v19
	v_lshrrev_b32_e32 v16, 16, v242
	v_and_or_b32 v43, v243, s22, v16
	ds_write_b128 v80, v[36:39] offset:34816
	ds_write_b128 v80, v[40:43] offset:34960
	s_cbranch_scc1 .LBB0_356
	s_cmp_ge_i32 s80, s19
	s_mov_b64 s[74:75], -1
	s_cbranch_scc0 .LBB0_351
	s_sub_i32 s22, s80, s19
	s_mul_i32 s22, s22, s13
	s_add_i32 s76, s22, s62
	s_ashr_i32 s22, s76, 2
	s_and_b32 s22, s22, -8
	s_add_i32 s93, s22, 0x4080
	s_mov_b64 s[74:75], 0

; template <int DK, int DV, bool SEPQ> ...
;     ...
;         for (int vt = 0; vt < NVT; ++vt) { const f32x4 s = S[ct][vt]; u32x2 w; w.x = cvt_pk_bf16(s[0], s[1]); w.y = cvt_pk_bf16(s[2], s[3]);
;             *(u32x2*)(ST + (16 * vt + fr) * LQ + 16 * (wid * NCTW + ct) + 4 * fq) = w; }
;     __syncthreads();
;     {
;         const float gi_i = GI[16 * m + fr];
;         const int n0 = 2 * hw, n1 = 2 * hw + 1; const bool do0 = n0 <= m, do1 = n1 <= m;
;         f32x4 acc0 = {0.f, 0.f, 0.f, 0.f}, acc1 = {0.f, 0.f, 0.f, 0.f};
; #pragma unroll
;         for (int vt = 0; vt < NVTW; ++vt) O[vt] = (f32x4){0.f, 0.f, 0.f, 0.f};
; #pragma unroll
;         for (int ks = 0; ks < DK / 32; ++ks) {
;             const bf16x8 qf = *(const bf16x8*)(QA + (16 * m + fr) * LQ + 32 * ks + 8 * fq);
;             if (do0) { const bf16x8 kf = *(const bf16x8*)(KB + (16 * n0 + fr) * LQ + 32 * ks + 8 * fq); acc0 = __builtin_amdgcn_mfma_f32_16x16x32_bf16(kf, qf, acc0, 0, 0, 0); }
;             if (do1) { const bf16x8 kf = *(const bf16x8*)(KB + (16 * n1 + fr) * LQ + 32 * ks + 8 * fq); acc1 = __builtin_amdgcn_mfma_f32_16x16x32_bf16(kf, qf, acc1, 0, 0, 0); }
;             bf16x8 qs = qf; if (SEPQ) qs = *(const bf16x8*)(QS + (16 * m + fr) * LQ + 32 * ks + 8 * fq);
; #pragma unroll
;             for (int vt = 0; vt < NVTW; ++vt) { const bf16x8 sf = *(const bf16x8*)(ST + (16 * (hw * NVTW + vt) + fr) * LQ + 32 * ks + 8 * fq); O[vt] = __builtin_amdgcn_mfma_f32_16x16x32_bf16(sf, qs, O[vt], 0, 0, 0); }
;         }
; #pragma unroll
;         for (int nn = 0; nn < 2; ++nn) {
;             const int n = 2 * hw + nn; const f32x4 acc = nn == 0 ? acc0 : acc1;
;             const f32x4 gj = *(const f32x4*)(GI + 16 * n + 4 * fq); const int i = 16 * m + fr, j0 = 16 * n + 4 * fq; float p[4];
; #pragma unroll
;             for (int e = 0; e < 4; ++e) p[e] = (j0 + e <= i) ? acc[e] * __expf(gi_i - gj[e]) : 0.f;
;             u32x2 w; w.x = cvt_pk_bf16(p[0], p[1]); w.y = cvt_pk_bf16(p[2], p[3]); *(u32x2*)(P + (16 * m + fr) * LJ + j0) = w;
;         }
;         const float ei = __expf(gi_i);
; #pragma unroll
;         for (int vt = 0; vt < NVTW; ++vt) O[vt] = O[vt] * ei;
;     }
; __device__ __forceinline__ void mamba_block(ArgsP a_, unsigned char* smem) { const ArgsP a = a_;
;     ...
;         if (i < len) { const float Dh = AIN(24)[hd];
; #pragma unroll
.LBB0_356:
	s_load_dwordx2 s[22:23], s[4:5], 0xc0
	v_add_u32_e32 v212, s72, v71
	v_ashrrev_i32_e32 v213, 31, v212
	v_lshlrev_b64 v[214:215], 11, v[212:213]
	v_lshlrev_b64 v[212:213], 13, v[212:213]
	v_readlane_b32 s74, v255, 12
	v_readlane_b32 s75, v255, 13
	v_lshl_or_b32 v216, s71, 6, v214
	v_or_b32_e32 v214, v216, v66
	s_nop 0
	v_lshl_add_u64 v[212:213], s[74:75], 0, v[212:213]
	s_lshl_b32 s74, s71, 7
	s_mov_b32 s75, s12
	v_lshl_add_u64 v[212:213], v[212:213], 0, s[74:75]
	v_lshlrev_b32_e32 v218, 1, v66
	v_mov_b32_e32 v219, 0
	v_lshl_add_u64 v[212:213], v[212:213], 0, v[218:219]
	v_lshlrev_b64 v[218:219], 1, v[214:215]
	global_load_dwordx2 v[202:203], v[212:213], off
	v_lshl_add_u64 v[218:219], s[24:25], 0, v[218:219]
	global_load_dwordx2 v[204:205], v[218:219], off
	global_load_dwordx2 v[206:207], v[212:213], off offset:32
	v_or_b32_e32 v214, v216, v68
	v_lshlrev_b64 v[218:219], 1, v[214:215]
	v_lshl_add_u64 v[218:219], s[24:25], 0, v[218:219]
	global_load_dwordx2 v[208:209], v[218:219], off
	s_lshl_b32 s74, s71, 2
	v_mov_b32_e32 v217, s74
	s_waitcnt lgkmcnt(0)
	global_load_dword v210, v217, s[22:23]
	v_cvt_pk_bf16_f32 v18, v20, v21
	v_cvt_pk_bf16_f32 v19, v22, v23
	ds_write_b64 v109, v[18:19]
	v_cvt_pk_bf16_f32 v18, v24, v25
	v_cvt_pk_bf16_f32 v19, v26, v27
	ds_write_b64 v109, v[18:19] offset:4352
	v_cvt_pk_bf16_f32 v18, v28, v29
	v_cvt_pk_bf16_f32 v19, v30, v31
	ds_write_b64 v109, v[18:19] offset:8704
	v_cvt_pk_bf16_f32 v18, v32, v33
	v_cvt_pk_bf16_f32 v19, v34, v35
	ds_write_b64 v109, v[18:19] offset:13056
	s_waitcnt lgkmcnt(0)
	s_barrier
	ds_read_b32 v123, v81
	ds_read_b128 v[220:223], v64
	ds_read_b128 v[224:227], v65 offset:17408
	ds_read_b128 v[228:231], v65 offset:21760
	ds_read_b128 v[232:235], v114
	ds_read_b128 v[236:239], v114 offset:4352
	ds_read_b128 v[164:167], v64 offset:64
	ds_read_b128 v[168:171], v65 offset:17472
	ds_read_b128 v[172:175], v65 offset:21824
	ds_read_b128 v[176:179], v114 offset:64
	ds_read_b128 v[180:183], v114 offset:4416
	s_waitcnt lgkmcnt(5)
	v_mfma_f32_16x16x32_bf16 v[40:43], v[224:227], v[220:223], 0
	v_mfma_f32_16x16x32_bf16 v[36:39], v[228:231], v[220:223], 0
	v_mfma_f32_16x16x32_bf16 v[44:47], v[232:235], v[220:223], 0
	v_mfma_f32_16x16x32_bf16 v[48:51], v[236:239], v[220:223], 0
	ds_read_b128 v[220:223], v64 offset:128
	ds_read_b128 v[224:227], v65 offset:17536
	ds_read_b128 v[228:231], v65 offset:21888
	ds_read_b128 v[232:235], v114 offset:128
	ds_read_b128 v[236:239], v114 offset:4480
	s_waitcnt lgkmcnt(5)
	v_mfma_f32_16x16x32_bf16 v[40:43], v[168:171], v[164:167], v[40:43]
	v_mfma_f32_16x16x32_bf16 v[36:39], v[172:175], v[164:167], v[36:39]
	v_mfma_f32_16x16x32_bf16 v[44:47], v[176:179], v[164:167], v[44:47]
	v_mfma_f32_16x16x32_bf16 v[48:51], v[180:183], v[164:167], v[48:51]
	ds_read_b128 v[164:167], v64 offset:192
	ds_read_b128 v[168:171], v65 offset:17600
	ds_read_b128 v[172:175], v65 offset:21952
	ds_read_b128 v[176:179], v114 offset:192
	ds_read_b128 v[180:183], v114 offset:4544
	s_waitcnt lgkmcnt(5)
	v_mfma_f32_16x16x32_bf16 v[40:43], v[224:227], v[220:223], v[40:43]
	v_mfma_f32_16x16x32_bf16 v[36:39], v[228:231], v[220:223], v[36:39]
	v_mfma_f32_16x16x32_bf16 v[44:47], v[232:235], v[220:223], v[44:47]
	v_mfma_f32_16x16x32_bf16 v[48:51], v[236:239], v[220:223], v[48:51]
	s_waitcnt lgkmcnt(0)
	v_mfma_f32_16x16x32_bf16 v[40:43], v[168:171], v[164:167], v[40:43]
	v_mfma_f32_16x16x32_bf16 v[36:39], v[172:175], v[164:167], v[36:39]
	v_mfma_f32_16x16x32_bf16 v[44:47], v[176:179], v[164:167], v[44:47]
	v_mfma_f32_16x16x32_bf16 v[48:51], v[180:183], v[164:167], v[48:51]
	s_nop 7
	v_cmp_gt_i32_e32 vcc, s73, v71
	ds_read_b128 v[52:55], v82
	s_waitcnt lgkmcnt(0)
	v_sub_f32_e32 v16, v123, v52
	v_mul_f32_e32 v16, 0x3fb8aa3b, v16
	v_exp_f32_e32 v16, v16
	v_sub_f32_e32 v18, v123, v53
	v_sub_f32_e32 v19, v123, v54
	v_mul_f32_e32 v18, 0x3fb8aa3b, v18
	v_mul_f32_e32 v16, v40, v16
	v_mul_f32_e32 v19, 0x3fb8aa3b, v19
	v_sub_f32_e32 v40, v123, v55
	v_exp_f32_e32 v18, v18
	v_exp_f32_e32 v19, v19
	v_mul_f32_e32 v40, 0x3fb8aa3b, v40
	v_exp_f32_e32 v40, v40
	v_mul_f32_e32 v18, v41, v18
	v_mul_f32_e32 v19, v42, v19
	v_cndmask_b32_e64 v18, 0, v18, s[48:49]
	v_cndmask_b32_e64 v19, v19, 0, s[50:51]
	v_mul_f32_e32 v40, v43, v40
	v_cndmask_b32_e64 v16, v16, 0, s[46:47]
	v_cndmask_b32_e64 v40, v40, 0, s[52:53]
	v_cvt_pk_bf16_f32 v18, v16, v18
	v_cvt_pk_bf16_f32 v19, v19, v40
	ds_write_b64 v83, v[18:19]
	ds_read_b128 v[40:43], v82 offset:64
	s_waitcnt lgkmcnt(0)
	v_sub_f32_e32 v16, v123, v40
	v_mul_f32_e32 v16, 0x3fb8aa3b, v16
	v_sub_f32_e32 v18, v123, v41
	v_exp_f32_e32 v16, v16
	v_mul_f32_e32 v18, 0x3fb8aa3b, v18
	v_exp_f32_e32 v18, v18
	v_sub_f32_e32 v19, v123, v42
	v_mul_f32_e32 v16, v36, v16
	v_sub_f32_e32 v36, v123, v43
	v_mul_f32_e32 v18, v37, v18
	v_mul_f32_e32 v19, 0x3fb8aa3b, v19
	v_mul_f32_e32 v36, 0x3fb8aa3b, v36
	v_cndmask_b32_e64 v16, v16, 0, s[54:55]
	v_cndmask_b32_e64 v18, 0, v18, s[56:57]
	v_exp_f32_e32 v19, v19
	v_exp_f32_e32 v36, v36
	v_cvt_pk_bf16_f32 v18, v16, v18
	v_mul_f32_e32 v16, 0x3fb8aa3b, v123
	v_exp_f32_e32 v16, v16
	v_mul_f32_e32 v19, v38, v19
	v_mul_f32_e32 v36, v39, v36
	v_cndmask_b32_e64 v19, v19, 0, s[58:59]
	v_cndmask_b32_e64 v36, v36, 0, s[60:61]
	v_cvt_pk_bf16_f32 v19, v19, v36
	ds_write_b64 v83, v[18:19] offset:32
	v_pk_mul_f32 v[36:37], v[16:17], v[44:45] op_sel_hi:[0,1]
	v_pk_mul_f32 v[38:39], v[16:17], v[46:47] op_sel_hi:[0,1]
	v_pk_mul_f32 v[40:41], v[16:17], v[48:49] op_sel_hi:[0,1]
	v_pk_mul_f32 v[42:43], v[16:17], v[50:51] op_sel_hi:[0,1]
	s_waitcnt lgkmcnt(0)
	s_barrier
; __device__ __forceinline__ unsigned cvt_pk_bf16(float lo, float hi) { unsigned r; asm("v_cvt_pk_bf16_f32 %0, %1, %2" : "=v"(r) : "v"(lo), "v"(hi)); return r; }
; template <int DK, int DV, bool SEPQ> ...
;     ...
; #pragma unroll
;     for (int ks = 0; ks < 2; ++ks) { const bf16x8 pf = *(const bf16x8*)(P + (16 * m + fr) * LJ + 32 * ks + 8 * fq);
; #pragma unroll
;         for (int vt = 0; vt < NVTW; ++vt) { const bf16x8 vf = *(const bf16x8*)(VT + (16 * (hw * NVTW + vt) + fr) * LJ + 32 * ks + 8 * fq); O[vt] = __builtin_amdgcn_mfma_f32_16x16x32_bf16(vf, pf, O[vt], 0, 0, 0); } }
; #pragma unroll
;     for (int ct = 0; ct < NCTW; ++ct) { const int ctg = wid * NCTW + ct; const f32x4 dec = *(const f32x4*)(SDEC + 16 * ctg + 4 * fq);
; #pragma unroll
;         for (int vt = 0; vt < NVT; ++vt) S[ct][vt] = S[ct][vt] * dec;
; #pragma unroll
;         for (int ks = 0; ks < 2; ++ks) { const bf16x8 kf = *(const bf16x8*)(KT + (16 * ctg + fr) * LJ + 32 * ks + 8 * fq);
; #pragma unroll
;             for (int vt = 0; vt < NVT; ++vt) { const bf16x8 vf = *(const bf16x8*)(VT2 + (16 * vt + fr) * LJ + 32 * ks + 8 * fq); S[ct][vt] = __builtin_amdgcn_mfma_f32_16x16x32_bf16(kf, vf, S[ct][vt], 0, 0, 0); } } }
; __device__ __forceinline__ void mamba_block(ArgsP a_, unsigned char* smem) { const ArgsP a = a_;
;     ...
;         if (i < len) { const float Dh = AIN(24)[hd];
; #pragma unroll
;             for (int vt = 0; vt < 2; ++vt) { const int v = 16 * (hw * 2 + vt) + 4 * fq; const size_t o = (size_t)(row0 + i) * 2048 + hd * 64 + v;
;                 const u32x2 xt = *(const u32x2*)(XC + (size_t)(row0 + i) * 4096 + hd * 64 + v); const u32x2 zt = *(const u32x2*)(ZG + o);
;                 const f32x4 xs = {__uint_as_float(xt.x << 16), __uint_as_float(xt.x & 0xffff0000u), __uint_as_float(xt.y << 16), __uint_as_float(xt.y & 0xffff0000u)};
;                 const f32x4 zg = {__uint_as_float(zt.x << 16), __uint_as_float(zt.x & 0xffff0000u), __uint_as_float(zt.y << 16), __uint_as_float(zt.y & 0xffff0000u)};
;                 const f32x4 y = (O[vt] + xs * Dh) * zg; *(u32x2*)(YB + o) = (u32x2){cvt_pk_bf16(y[0], y[1]), cvt_pk_bf16(y[2], y[3])}; } }
	ds_read_b128 v[220:223], v84
	ds_read_b128 v[224:227], v110 offset:53248
	ds_read_b128 v[228:231], v110 offset:55552
	ds_read_b128 v[232:235], v84 offset:64
	ds_read_b128 v[236:239], v110 offset:53312
	ds_read_b128 v[240:243], v110 offset:55616
	ds_read_b128 v[244:247], v111
	ds_read_b128 v[248:251], v70 offset:34816
	ds_read_b128 v[164:167], v112 offset:62464
	ds_read_b128 v[168:171], v112 offset:64768
	ds_read_b128 v[172:175], v113 offset:62464
	ds_read_b128 v[176:179], v113 offset:64768
	ds_read_b128 v[180:183], v70 offset:34880
	s_waitcnt lgkmcnt(11)
	v_mfma_f32_16x16x32_bf16 v[36:39], v[224:227], v[220:223], v[36:39]
	ds_read_b128 v[224:227], v112 offset:62528
	s_waitcnt lgkmcnt(11)
	v_mfma_f32_16x16x32_bf16 v[44:47], v[228:231], v[220:223], v[40:43]
	ds_read_b128 v[220:223], v112 offset:64832
	ds_read_b128 v[228:231], v113 offset:62528
	s_nop 1
	s_waitcnt lgkmcnt(11)
	v_mfma_f32_16x16x32_bf16 v[40:43], v[236:239], v[232:235], v[36:39]
	ds_read_b128 v[236:239], v113 offset:64832
	s_nop 2
	s_waitcnt lgkmcnt(11)
	v_mfma_f32_16x16x32_bf16 v[36:39], v[240:243], v[232:235], v[44:47]
	s_nop 2
	s_waitcnt lgkmcnt(10)
	v_pk_mul_f32 v[22:23], v[22:23], v[246:247]
	v_pk_mul_f32 v[20:21], v[20:21], v[244:245]
	v_pk_mul_f32 v[24:25], v[24:25], v[244:245]
	v_pk_mul_f32 v[26:27], v[26:27], v[246:247]
	v_pk_mul_f32 v[28:29], v[28:29], v[244:245]
	v_pk_mul_f32 v[30:31], v[30:31], v[246:247]
	v_pk_mul_f32 v[32:33], v[32:33], v[244:245]
	v_pk_mul_f32 v[34:35], v[34:35], v[246:247]
	s_waitcnt lgkmcnt(8)
	v_mfma_f32_16x16x32_bf16 v[18:21], v[248:251], v[164:167], v[20:23]
	s_waitcnt lgkmcnt(7)
	v_mfma_f32_16x16x32_bf16 v[24:27], v[248:251], v[168:171], v[24:27]
	s_waitcnt lgkmcnt(6)
	v_mfma_f32_16x16x32_bf16 v[28:31], v[248:251], v[172:175], v[28:31]
	s_waitcnt lgkmcnt(5)
	v_mfma_f32_16x16x32_bf16 v[32:35], v[248:251], v[176:179], v[32:35]
	s_waitcnt lgkmcnt(3)
	v_mfma_f32_16x16x32_bf16 v[20:23], v[180:183], v[224:227], v[18:21]
	s_waitcnt lgkmcnt(2)
	v_mfma_f32_16x16x32_bf16 v[24:27], v[180:183], v[220:223], v[24:27]
	s_waitcnt lgkmcnt(1)
	v_mfma_f32_16x16x32_bf16 v[28:31], v[180:183], v[228:231], v[28:31]
	s_waitcnt lgkmcnt(0)
	v_mfma_f32_16x16x32_bf16 v[32:35], v[180:183], v[236:239], v[32:35]
	s_and_saveexec_b64 s[74:75], vcc
	s_cbranch_execz .LBB0_374
	v_add_u32_e32 v44, s72, v71
	v_ashrrev_i32_e32 v45, 31, v44
	s_waitcnt vmcnt(0)
	v_mov_b32_e32 v18, v210
	v_readlane_b32 s22, v255, 12
	v_lshlrev_b64 v[46:47], 11, v[44:45]
	v_lshlrev_b64 v[44:45], 13, v[44:45]
	v_readlane_b32 s23, v255, 13
	v_lshl_or_b32 v19, s71, 6, v46
	v_or_b32_e32 v46, v19, v66
	v_lshl_add_u64 v[44:45], s[22:23], 0, v[44:45]
	s_lshl_b32 s22, s71, 7
	s_mov_b32 s23, s12
	v_lshl_add_u64 v[44:45], v[44:45], 0, s[22:23]
	v_lshlrev_b32_e32 v16, 1, v66
	v_lshl_add_u64 v[44:45], v[44:45], 0, v[16:17]
	v_lshlrev_b64 v[50:51], 1, v[46:47]
	v_mov_b32_e32 v48, v202
	v_mov_b32_e32 v49, v203
	v_lshl_add_u64 v[52:53], s[24:25], 0, v[50:51]
	v_mov_b32_e32 v52, v204
	v_mov_b32_e32 v53, v205
	v_or_b32_e32 v46, v19, v68
	v_lshlrev_b32_e32 v54, 16, v48
	v_and_b32_e32 v55, 0xffff0000, v48
	v_lshlrev_b32_e32 v48, 16, v49
	v_and_b32_e32 v49, 0xffff0000, v49
	v_lshlrev_b32_e32 v124, 16, v52
	v_and_b32_e32 v125, 0xffff0000, v52
	v_lshlrev_b32_e32 v52, 16, v53
	v_and_b32_e32 v53, 0xffff0000, v53
	v_pk_fma_f32 v[40:41], v[18:19], v[54:55], v[40:41] op_sel_hi:[0,1,1]
	v_pk_fma_f32 v[42:43], v[18:19], v[48:49], v[42:43] op_sel_hi:[0,1,1]
	v_pk_mul_f32 v[42:43], v[42:43], v[52:53]
	v_pk_mul_f32 v[40:41], v[40:41], v[124:125]
	s_nop 0
	v_cvt_pk_bf16_f32 v40, v40, v41
	v_cvt_pk_bf16_f32 v41, v42, v43
	v_lshl_add_u64 v[42:43], s[26:27], 0, v[50:51]
	global_store_dwordx2 v[42:43], v[40:41], off
	v_lshlrev_b64 v[42:43], 1, v[46:47]
	v_mov_b32_e32 v40, v206
	v_mov_b32_e32 v41, v207
	v_lshl_add_u64 v[44:45], s[24:25], 0, v[42:43]
	v_mov_b32_e32 v44, v208
	v_mov_b32_e32 v45, v209
	v_lshlrev_b32_e32 v46, 16, v40
	v_and_b32_e32 v47, 0xffff0000, v40
	v_lshlrev_b32_e32 v40, 16, v41
	v_and_b32_e32 v41, 0xffff0000, v41
	v_lshlrev_b32_e32 v48, 16, v44
	v_and_b32_e32 v49, 0xffff0000, v44
	v_lshlrev_b32_e32 v44, 16, v45
	v_and_b32_e32 v45, 0xffff0000, v45
	v_pk_fma_f32 v[36:37], v[18:19], v[46:47], v[36:37] op_sel_hi:[0,1,1]
	v_pk_fma_f32 v[18:19], v[18:19], v[40:41], v[38:39] op_sel_hi:[0,1,1]
	v_pk_mul_f32 v[18:19], v[18:19], v[44:45]
	v_pk_mul_f32 v[36:37], v[36:37], v[48:49]
	s_nop 0
	v_cvt_pk_bf16_f32 v36, v36, v37
	v_cvt_pk_bf16_f32 v37, v18, v19
	v_lshl_add_u64 v[18:19], s[26:27], 0, v[42:43]
	global_store_dwordx2 v[18:19], v[36:37], off

; __device__ __forceinline__ void hg_block(ArgsP a_, int jl, unsigned char* smem) { const ArgsP a = a_;
;     ...
;         { f32x4 run = {0.f, 0.f, 0.f, 0.f};
; #pragma unroll
;           for (int r = 0; r < 4; ++r) { run = run + lf4[r]; cs[r] = run; }
;           *(f32x4*)(TOT + rg * 128 + c4) = run; }
;         __syncthreads();
;         { f32x4 pre = {0.f, 0.f, 0.f, 0.f}, gmid = pre, glast = pre;
; #pragma unroll
;           for (int k = 0; k < 16; ++k) { const f32x4 t = *(const f32x4*)(TOT + k * 128 + c4); if (k < rg) pre = pre + t; if (k < 8) gmid = gmid + t; glast = glast + t; }
.LBB0_412:
	s_waitcnt vmcnt(0)
	s_cmp_eq_u32 s64, 64
	s_cbranch_scc1 .Lhg_mask_done
	v_cmp_gt_i32_e32 vcc, s64, v136
	s_nop 1
	v_cndmask_b32_e32 v0, 0, v0, vcc
	v_cndmask_b32_e32 v1, 0, v1, vcc
	v_cndmask_b32_e32 v2, 0, v2, vcc
	v_cndmask_b32_e32 v3, 0, v3, vcc
	v_cndmask_b32_e32 v82, 0, v82, vcc
	v_cndmask_b32_e32 v83, 0, v83, vcc
	v_cndmask_b32_e32 v78, 0, v78, vcc
	v_cndmask_b32_e32 v79, 0, v79, vcc
	v_cndmask_b32_e32 v80, 0, v80, vcc
	v_cndmask_b32_e32 v81, 0, v81, vcc
	v_cmp_gt_i32_e32 vcc, s64, v107
	s_nop 1
	v_cndmask_b32_e32 v4, 0, v4, vcc
	v_cndmask_b32_e32 v5, 0, v5, vcc
	v_cndmask_b32_e32 v6, 0, v6, vcc
	v_cndmask_b32_e32 v7, 0, v7, vcc
	v_cndmask_b32_e32 v90, 0, v90, vcc
	v_cndmask_b32_e32 v91, 0, v91, vcc
	v_cndmask_b32_e32 v86, 0, v86, vcc
	v_cndmask_b32_e32 v87, 0, v87, vcc
	v_cndmask_b32_e32 v88, 0, v88, vcc
	v_cndmask_b32_e32 v89, 0, v89, vcc
	v_cmp_gt_i32_e32 vcc, s64, v109
	s_nop 1
	v_cndmask_b32_e32 v8, 0, v8, vcc
	v_cndmask_b32_e32 v9, 0, v9, vcc
	v_cndmask_b32_e32 v10, 0, v10, vcc
	v_cndmask_b32_e32 v11, 0, v11, vcc
	v_cndmask_b32_e32 v102, 0, v102, vcc
	v_cndmask_b32_e32 v103, 0, v103, vcc
	v_cndmask_b32_e32 v98, 0, v98, vcc
	v_cndmask_b32_e32 v99, 0, v99, vcc
	v_cndmask_b32_e32 v100, 0, v100, vcc
	v_cndmask_b32_e32 v101, 0, v101, vcc
	v_cmp_gt_i32_e32 vcc, s64, v164
	s_nop 1
	v_cndmask_b32_e32 v12, 0, v12, vcc
	v_cndmask_b32_e32 v13, 0, v13, vcc
	v_cndmask_b32_e32 v14, 0, v14, vcc
	v_cndmask_b32_e32 v15, 0, v15, vcc
	v_cndmask_b32_e32 v120, 0, v120, vcc
	v_cndmask_b32_e32 v121, 0, v121, vcc
	v_cndmask_b32_e32 v110, 0, v110, vcc
	v_cndmask_b32_e32 v111, 0, v111, vcc
	v_cndmask_b32_e32 v112, 0, v112, vcc
	v_cndmask_b32_e32 v113, 0, v113, vcc
.Lhg_mask_done:
	v_pk_add_f32 v[62:63], v[2:3], 0 op_sel_hi:[1,0]
	v_pk_add_f32 v[64:65], v[0:1], 0 op_sel_hi:[1,0]
	v_pk_add_f32 v[58:59], v[62:63], v[6:7]
	v_pk_add_f32 v[60:61], v[64:65], v[4:5]
	v_pk_add_f32 v[54:55], v[58:59], v[10:11]
	v_pk_add_f32 v[56:57], v[60:61], v[8:9]
	v_pk_add_f32 v[52:53], v[54:55], v[14:15]
	v_pk_add_f32 v[50:51], v[56:57], v[12:13]
	ds_write_b128 v168, v[50:53]
	s_waitcnt vmcnt(0) lgkmcnt(0)
	s_barrier
	ds_read_b128 v[202:205], v135
	ds_read_b128 v[206:209], v135 offset:512
	ds_read_b128 v[210:213], v135 offset:1024
	ds_read_b128 v[214:217], v135 offset:1536
	ds_read_b128 v[218:221], v135 offset:2048
	ds_read_b128 v[222:225], v135 offset:2560
	ds_read_b128 v[226:229], v135 offset:3072
	ds_read_b128 v[230:233], v135 offset:3584
	ds_read_b128 v[234:237], v135 offset:4096
	ds_read_b128 v[238:241], v135 offset:4608
	ds_read_b128 v[242:245], v135 offset:5120
	ds_read_b128 v[246:249], v135 offset:5632
	v_lshlrev_b32_e32 v175, 16, v78
	v_and_b32_e32 v178, 0xffff0000, v79
	s_mov_b32 s49, 0xffff0000
	s_waitcnt lgkmcnt(11)
	v_pk_add_f32 v[70:71], v[204:205], 0 op_sel_hi:[1,0]
	v_pk_add_f32 v[72:73], v[202:203], 0 op_sel_hi:[1,0]
	ds_read_b128 v[202:205], v135 offset:6144
	v_cndmask_b32_e64 v75, 0, v73, s[66:67]
	v_cndmask_b32_e64 v74, 0, v72, s[66:67]
	v_cndmask_b32_e64 v77, 0, v71, s[66:67]
	v_cndmask_b32_e64 v76, 0, v70, s[66:67]
	s_waitcnt lgkmcnt(11)
	v_pk_add_f32 v[126:127], v[206:207], v[74:75]
	v_pk_add_f32 v[128:129], v[208:209], v[76:77]
	v_pk_add_f32 v[70:71], v[70:71], v[208:209]
	v_pk_add_f32 v[72:73], v[72:73], v[206:207]
	ds_read_b128 v[206:209], v135 offset:6656
	v_cndmask_b32_e64 v75, v75, v127, s[68:69]
	v_cndmask_b32_e64 v74, v74, v126, s[68:69]
	v_cndmask_b32_e64 v77, v77, v129, s[68:69]
	v_cndmask_b32_e64 v76, v76, v128, s[68:69]
	s_waitcnt lgkmcnt(11)
	v_pk_add_f32 v[126:127], v[210:211], v[74:75]
	v_pk_add_f32 v[128:129], v[212:213], v[76:77]
	v_pk_add_f32 v[70:71], v[70:71], v[212:213]
	v_pk_add_f32 v[72:73], v[72:73], v[210:211]
	ds_read_b128 v[210:213], v135 offset:7168
	v_cndmask_b32_e64 v75, v75, v127, s[70:71]
	v_cndmask_b32_e64 v74, v74, v126, s[70:71]
	v_cndmask_b32_e64 v77, v77, v129, s[70:71]
	v_cndmask_b32_e64 v76, v76, v128, s[70:71]
	s_waitcnt lgkmcnt(11)
	v_pk_add_f32 v[126:127], v[214:215], v[74:75]
	v_pk_add_f32 v[128:129], v[216:217], v[76:77]
	v_pk_add_f32 v[70:71], v[70:71], v[216:217]
	v_pk_add_f32 v[72:73], v[72:73], v[214:215]
	ds_read_b128 v[214:217], v135 offset:7680
	v_cndmask_b32_e64 v75, v75, v127, s[72:73]
	v_cndmask_b32_e64 v74, v74, v126, s[72:73]
	v_cndmask_b32_e64 v77, v77, v129, s[72:73]
	v_cndmask_b32_e64 v76, v76, v128, s[72:73]
	s_waitcnt lgkmcnt(11)
	v_pk_add_f32 v[126:127], v[218:219], v[74:75]
	v_pk_add_f32 v[128:129], v[220:221], v[76:77]
	v_pk_add_f32 v[70:71], v[70:71], v[220:221]
	v_pk_add_f32 v[72:73], v[72:73], v[218:219]
	v_cndmask_b32_e64 v75, v75, v127, s[74:75]
	v_cndmask_b32_e64 v74, v74, v126, s[74:75]
	v_cndmask_b32_e64 v77, v77, v129, s[74:75]
	v_cndmask_b32_e64 v76, v76, v128, s[74:75]
	s_waitcnt lgkmcnt(10)
	v_pk_add_f32 v[126:127], v[222:223], v[74:75]
	v_pk_add_f32 v[128:129], v[224:225], v[76:77]
	v_pk_add_f32 v[70:71], v[70:71], v[224:225]
	v_pk_add_f32 v[72:73], v[72:73], v[222:223]
	v_cndmask_b32_e64 v75, v75, v127, s[76:77]
	v_cndmask_b32_e64 v74, v74, v126, s[76:77]
	v_cndmask_b32_e64 v77, v77, v129, s[76:77]
	v_cndmask_b32_e64 v76, v76, v128, s[76:77]
	s_waitcnt lgkmcnt(9)
	v_pk_add_f32 v[126:127], v[226:227], v[74:75]
	v_pk_add_f32 v[128:129], v[228:229], v[76:77]
	v_cndmask_b32_e64 v75, v75, v127, s[78:79]
	v_cndmask_b32_e64 v74, v74, v126, s[78:79]
	v_pk_add_f32 v[126:127], v[70:71], v[228:229]
	v_cndmask_b32_e64 v77, v77, v129, s[78:79]
	v_cndmask_b32_e64 v76, v76, v128, s[78:79]
	v_pk_add_f32 v[72:73], v[72:73], v[226:227]
	s_waitcnt lgkmcnt(8)
; __device__ __forceinline__ unsigned cvt_pk_bf16(float lo, float hi) { unsigned r; asm("v_cvt_pk_bf16_f32 %0, %1, %2" : "=v"(r) : "v"(lo), "v"(hi)); return r; }
; __device__ __forceinline__ void hg_block(ArgsP a_, int jl, unsigned char* smem) { const ArgsP a = a_;
;     ...
;           for (int k = 0; k < 16; ++k) { const f32x4 t = *(const f32x4*)(TOT + k * 128 + c4); if (k < rg) pre = pre + t; if (k < 8) gmid = gmid + t; glast = glast + t; }
;           f32x4 Emid, Elm;
; #pragma unroll
;           for (int e = 0; e < 4; ++e) { Emid[e] = __expf(gmid[e]); Elm[e] = __expf(glast[e] - gmid[e]); }
;           float ktv[4][4];
; #pragma unroll
;           for (int r = 0; r < 4; ++r) { const int i = 4 * rg + r; const f32x4 d = pre + cs[r] - gmid;
;               const f32x4 q = {__uint_as_float(q2[r].x << 16), __uint_as_float(q2[r].x & 0xffff0000u), __uint_as_float(q2[r].y << 16), __uint_as_float(q2[r].y & 0xffff0000u)};
;               const f32x4 kk = {__uint_as_float(kk2[r].x << 16), __uint_as_float(kk2[r].x & 0xffff0000u), __uint_as_float(kk2[r].y << 16), __uint_as_float(kk2[r].y & 0xffff0000u)};
;               f32x4 qa, qs, kb;
; #pragma unroll
;               for (int e = 0; e < 4; ++e) { const float eq = __expf(d[e]), ek = __expf(-d[e]); qa[e] = q[e] * eq; qs[e] = qa[e] * Emid[e]; kb[e] = kk[e] * ek; ktv[r][e] = kb[e] * Elm[e]; }
;               *(u32x2*)(QA + i * LQ + c4) = (u32x2){cvt_pk_bf16(qa[0], qa[1]), cvt_pk_bf16(qa[2], qa[3])};
;               *(u32x2*)(QS + i * LQ + c4) = (u32x2){cvt_pk_bf16(qs[0], qs[1]), cvt_pk_bf16(qs[2], qs[3])};
;               *(u32x2*)(KB + i * LQ + c4) = (u32x2){cvt_pk_bf16(kb[0], kb[1]), cvt_pk_bf16(kb[2], kb[3])}; }
	v_pk_add_f32 v[66:67], v[230:231], v[74:75]
	v_pk_add_f32 v[128:129], v[232:233], v[76:77]
	v_cndmask_b32_e64 v75, v75, v67, s[80:81]
	v_cndmask_b32_e64 v74, v74, v66, s[80:81]
	v_pk_add_f32 v[66:67], v[126:127], v[232:233]
	v_pk_add_f32 v[68:69], v[72:73], v[230:231]
	v_cndmask_b32_e64 v77, v77, v129, s[80:81]
	v_cndmask_b32_e64 v76, v76, v128, s[80:81]
	v_mul_f32_e32 v16, 0x3fb8aa3b, v68
	v_mul_f32_e32 v119, 0x3fb8aa3b, v66
	s_waitcnt lgkmcnt(7)
	v_pk_add_f32 v[126:127], v[234:235], v[74:75]
	v_pk_add_f32 v[128:129], v[236:237], v[76:77]
	v_cndmask_b32_e64 v75, v75, v127, s[82:83]
	v_cndmask_b32_e64 v74, v74, v126, s[82:83]
	v_cndmask_b32_e64 v77, v77, v129, s[82:83]
	v_cndmask_b32_e64 v76, v76, v128, s[82:83]
	v_pk_add_f32 v[126:127], v[66:67], v[236:237]
	v_pk_add_f32 v[128:129], v[68:69], v[234:235]
	v_exp_f32_e32 v16, v16
	v_exp_f32_e32 v119, v119
	s_waitcnt lgkmcnt(6)
	v_pk_add_f32 v[130:131], v[238:239], v[74:75]
	v_pk_add_f32 v[132:133], v[240:241], v[76:77]
	v_pk_add_f32 v[126:127], v[126:127], v[240:241]
	v_pk_add_f32 v[128:129], v[128:129], v[238:239]
	v_cndmask_b32_e64 v75, v75, v131, s[84:85]
	v_cndmask_b32_e64 v74, v74, v130, s[84:85]
	v_cndmask_b32_e64 v77, v77, v133, s[84:85]
	v_cndmask_b32_e64 v76, v76, v132, s[84:85]
	s_waitcnt lgkmcnt(5)
	v_pk_add_f32 v[130:131], v[242:243], v[74:75]
	v_pk_add_f32 v[132:133], v[244:245], v[76:77]
	v_pk_add_f32 v[126:127], v[126:127], v[244:245]
	v_pk_add_f32 v[128:129], v[128:129], v[242:243]
	v_cndmask_b32_e64 v75, v75, v131, s[86:87]
	v_cndmask_b32_e64 v74, v74, v130, s[86:87]
	v_cndmask_b32_e64 v77, v77, v133, s[86:87]
	v_cndmask_b32_e64 v76, v76, v132, s[86:87]
	s_waitcnt lgkmcnt(4)
	v_pk_add_f32 v[130:131], v[246:247], v[74:75]
	v_pk_add_f32 v[132:133], v[248:249], v[76:77]
	v_pk_add_f32 v[126:127], v[126:127], v[248:249]
	v_pk_add_f32 v[128:129], v[128:129], v[246:247]
	v_cndmask_b32_e64 v75, v75, v131, s[88:89]
	v_cndmask_b32_e64 v74, v74, v130, s[88:89]
	v_cndmask_b32_e64 v77, v77, v133, s[88:89]
	v_cndmask_b32_e64 v76, v76, v132, s[88:89]
	s_waitcnt lgkmcnt(3)
	v_pk_add_f32 v[130:131], v[202:203], v[74:75]
	v_pk_add_f32 v[132:133], v[204:205], v[76:77]
	v_pk_add_f32 v[126:127], v[126:127], v[204:205]
	v_pk_add_f32 v[128:129], v[128:129], v[202:203]
	v_cndmask_b32_e64 v75, v75, v131, s[90:91]
	v_cndmask_b32_e64 v74, v74, v130, s[90:91]
	v_cndmask_b32_e64 v77, v77, v133, s[90:91]
	v_cndmask_b32_e64 v76, v76, v132, s[90:91]
	s_waitcnt lgkmcnt(2)
	v_pk_add_f32 v[130:131], v[206:207], v[74:75]
	v_pk_add_f32 v[132:133], v[208:209], v[76:77]
	v_pk_add_f32 v[126:127], v[126:127], v[208:209]
	v_pk_add_f32 v[128:129], v[128:129], v[206:207]
	v_cndmask_b32_e64 v75, v75, v131, s[92:93]
	v_cndmask_b32_e64 v74, v74, v130, s[92:93]
	v_cndmask_b32_e64 v77, v77, v133, s[92:93]
	v_cndmask_b32_e64 v76, v76, v132, s[92:93]
	s_waitcnt lgkmcnt(1)
	v_pk_add_f32 v[130:131], v[210:211], v[74:75]
	v_pk_add_f32 v[132:133], v[212:213], v[76:77]
	v_cndmask_b32_e64 v131, v75, v131, s[94:95]
	v_cndmask_b32_e64 v130, v74, v130, s[94:95]
	v_pk_add_f32 v[126:127], v[126:127], v[212:213]
	v_cndmask_b32_e64 v77, v77, v133, s[94:95]
	v_cndmask_b32_e64 v76, v76, v132, s[94:95]
	v_pk_add_f32 v[128:129], v[128:129], v[210:211]
	s_waitcnt lgkmcnt(0)
	v_pk_add_f32 v[132:133], v[214:215], v[130:131]
	v_pk_add_f32 v[72:73], v[128:129], v[214:215]
	v_cndmask_b32_e64 v129, v130, v132, s[96:97]
	v_add_f32_e32 v64, v64, v129
	v_sub_f32_e32 v64, v64, v68
	v_mul_f32_e32 v179, 0x3fb8aa3b, v64
	v_mul_f32_e32 v64, 0xbfb8aa3b, v64
	v_exp_f32_e32 v64, v64
	v_cndmask_b32_e64 v128, v131, v133, s[96:97]
	v_pk_add_f32 v[176:177], v[216:217], v[76:77]
	v_pk_add_f32 v[70:71], v[126:127], v[216:217]
	v_mul_f32_e32 v175, v64, v175
	v_add_f32_e32 v64, v65, v128
	v_sub_f32_e32 v64, v64, v69
	v_mul_f32_e32 v65, 0x3fb8aa3b, v64
	v_mul_f32_e32 v64, 0xbfb8aa3b, v64
	v_exp_f32_e32 v64, v64
	v_cndmask_b32_e64 v76, v76, v176, s[96:97]
	v_add_f32_e32 v62, v62, v76
	v_and_b32_e32 v176, 0xffff0000, v78
	v_sub_f32_e32 v62, v62, v66
	v_mul_f32_e32 v176, v64, v176
	v_mul_f32_e32 v64, 0x3fb8aa3b, v62
	v_mul_f32_e32 v62, 0xbfb8aa3b, v62
	v_exp_f32_e32 v62, v62
	v_cndmask_b32_e64 v77, v77, v177, s[96:97]
	v_lshlrev_b32_e32 v177, 16, v79
	v_sub_f32_e32 v74, v72, v68
	v_mul_f32_e32 v177, v62, v177
	v_add_f32_e32 v62, v63, v77
	v_sub_f32_e32 v62, v62, v67
	v_mul_f32_e32 v63, 0x3fb8aa3b, v62
	v_mul_f32_e32 v75, 0x3fb8aa3b, v69
	v_mul_f32_e32 v126, 0x3fb8aa3b, v67
	v_exp_f32_e32 v179, v179
	v_exp_f32_e32 v65, v65
	v_exp_f32_e32 v64, v64
	v_exp_f32_e32 v63, v63
	v_mul_f32_e32 v74, 0x3fb8aa3b, v74
	v_exp_f32_e32 v75, v75
	v_exp_f32_e32 v126, v126
	v_mul_f32_e32 v62, 0xbfb8aa3b, v62
	v_exp_f32_e32 v74, v74
	v_exp_f32_e32 v62, v62
	v_lshlrev_b32_e32 v130, 16, v80
	v_and_b32_e32 v131, 0xffff0000, v80
	v_lshlrev_b32_e32 v132, 16, v81
	v_and_b32_e32 v133, 0xffff0000, v81
	v_mul_f32_e32 v130, v179, v130
	v_mul_f32_e32 v65, v65, v131
	v_mul_f32_e32 v64, v64, v132
	v_mul_f32_e32 v63, v63, v133
	v_add_f32_e32 v60, v60, v129
	v_mul_f32_e32 v179, v16, v130
	v_mul_f32_e32 v131, v75, v65
	v_mul_f32_e32 v132, v119, v64
	v_mul_f32_e32 v133, v126, v63
	v_cvt_pk_bf16_f32 v63, v64, v63
	v_cvt_pk_bf16_f32 v64, v179, v131
	v_sub_f32_e32 v60, v60, v68
	v_mul_f32_e32 v180, v74, v175
	v_mul_f32_e32 v178, v62, v178
	v_cvt_pk_bf16_f32 v62, v130, v65
	v_cvt_pk_bf16_f32 v65, v132, v133
	ds_write_b64 v106, v[64:65] offset:34816
	v_cvt_pk_bf16_f32 v64, v175, v176
	v_mul_f32_e32 v175, 0x3fb8aa3b, v60
	v_mul_f32_e32 v60, 0xbfb8aa3b, v60
	v_exp_f32_e32 v60, v60
	v_lshlrev_b32_e32 v130, 16, v86
	v_add_f32_e32 v58, v58, v76
	v_and_b32_e32 v131, 0xffff0000, v86
	v_mul_f32_e32 v130, v60, v130
; __device__ __forceinline__ unsigned cvt_pk_bf16(float lo, float hi) { unsigned r; asm("v_cvt_pk_bf16_f32 %0, %1, %2" : "=v"(r) : "v"(lo), "v"(hi)); return r; }
; __device__ __forceinline__ void hg_block(ArgsP a_, int jl, unsigned char* smem) { const ArgsP a = a_;
;     ...
;           for (int r = 0; r < 4; ++r) { const int i = 4 * rg + r; const f32x4 d = pre + cs[r] - gmid;
;               const f32x4 q = {__uint_as_float(q2[r].x << 16), __uint_as_float(q2[r].x & 0xffff0000u), __uint_as_float(q2[r].y << 16), __uint_as_float(q2[r].y & 0xffff0000u)};
;               const f32x4 kk = {__uint_as_float(kk2[r].x << 16), __uint_as_float(kk2[r].x & 0xffff0000u), __uint_as_float(kk2[r].y << 16), __uint_as_float(kk2[r].y & 0xffff0000u)};
;               f32x4 qa, qs, kb;
; #pragma unroll
;               for (int e = 0; e < 4; ++e) { const float eq = __expf(d[e]), ek = __expf(-d[e]); qa[e] = q[e] * eq; qs[e] = qa[e] * Emid[e]; kb[e] = kk[e] * ek; ktv[r][e] = kb[e] * Elm[e]; }
;               *(u32x2*)(QA + i * LQ + c4) = (u32x2){cvt_pk_bf16(qa[0], qa[1]), cvt_pk_bf16(qa[2], qa[3])};
;               *(u32x2*)(QS + i * LQ + c4) = (u32x2){cvt_pk_bf16(qs[0], qs[1]), cvt_pk_bf16(qs[2], qs[3])};
;               *(u32x2*)(KB + i * LQ + c4) = (u32x2){cvt_pk_bf16(kb[0], kb[1]), cvt_pk_bf16(kb[2], kb[3])}; }
; #pragma unroll
;           for (int e = 0; e < 4; ++e) {
;               *(u32x2*)(KT + (c4 + e) * LJ + 4 * rg) = (u32x2){cvt_pk_bf16(ktv[0][e], ktv[1][e]), cvt_pk_bf16(ktv[2][e], ktv[3][e])};
;               unsigned vv[4];
; #pragma unroll
;               for (int r = 0; r < 4; ++r) { const unsigned w = (e < 2) ? v2[r].x : v2[r].y; vv[r] = (e & 1) ? (w >> 16) : (w & 0xffffu); }
;               *(u32x2*)(VT + (c4 + e) * LJ + 4 * rg) = (u32x2){vv[0] | (vv[1] << 16), vv[2] | (vv[3] << 16)}; }
;           if (rg == 0) { f32x4 sd;
; #pragma unroll
;               for (int e = 0; e < 4; ++e) sd[e] = __expf(glast[e]);
;               *(f32x4*)(SDEC + c4) = sd; } }
	v_add_f32_e32 v60, v61, v128
	v_sub_f32_e32 v60, v60, v69
	v_mul_f32_e32 v61, 0x3fb8aa3b, v60
	v_mul_f32_e32 v60, 0xbfb8aa3b, v60
	v_exp_f32_e32 v60, v60
	v_sub_f32_e32 v58, v58, v66
	v_lshlrev_b32_e32 v132, 16, v87
	v_sub_f32_e32 v117, v73, v69
	v_mul_f32_e32 v131, v60, v131
	v_mul_f32_e32 v60, 0x3fb8aa3b, v58
	v_mul_f32_e32 v58, 0xbfb8aa3b, v58
	v_exp_f32_e32 v58, v58
	v_exp_f32_e32 v175, v175
	v_exp_f32_e32 v61, v61
	v_exp_f32_e32 v60, v60
	v_mul_f32_e32 v132, v58, v132
	v_add_f32_e32 v58, v59, v77
	v_sub_f32_e32 v58, v58, v67
	v_mul_f32_e32 v59, 0x3fb8aa3b, v58
	v_exp_f32_e32 v59, v59
	v_mul_f32_e32 v117, 0x3fb8aa3b, v117
	v_mul_f32_e32 v58, 0xbfb8aa3b, v58
	v_exp_f32_e32 v117, v117
	v_cvt_pk_bf16_f32 v65, v177, v178
	v_exp_f32_e32 v58, v58
	ds_write2st64_b64 v106, v[62:63], v[64:65] offset1:34
	v_lshlrev_b32_e32 v62, 16, v88
	v_and_b32_e32 v63, 0xffff0000, v88
	v_lshlrev_b32_e32 v64, 16, v89
	v_and_b32_e32 v65, 0xffff0000, v89
	v_mul_f32_e32 v62, v175, v62
	v_mul_f32_e32 v61, v61, v63
	v_mul_f32_e32 v60, v60, v64
	v_mul_f32_e32 v59, v59, v65
	v_add_f32_e32 v56, v56, v129
	v_and_b32_e32 v133, 0xffff0000, v87
	v_mul_f32_e32 v175, v16, v62
	v_mul_f32_e32 v63, v75, v61
	v_mul_f32_e32 v64, v119, v60
	v_mul_f32_e32 v65, v126, v59
	v_cvt_pk_bf16_f32 v59, v60, v59
	v_cvt_pk_bf16_f32 v60, v175, v63
	v_sub_f32_e32 v56, v56, v68
	v_mul_f32_e32 v181, v117, v176
	v_mul_f32_e32 v176, v74, v130
	v_mul_f32_e32 v133, v58, v133
	v_cvt_pk_bf16_f32 v58, v62, v61
	v_cvt_pk_bf16_f32 v61, v64, v65
	ds_write_b64 v108, v[60:61] offset:34816
	v_cvt_pk_bf16_f32 v60, v130, v131
	v_mul_f32_e32 v130, 0x3fb8aa3b, v56
	v_mul_f32_e32 v56, 0xbfb8aa3b, v56
	v_exp_f32_e32 v56, v56
	v_lshlrev_b32_e32 v62, 16, v98
	v_add_f32_e32 v54, v54, v76
	v_and_b32_e32 v63, 0xffff0000, v98
	v_mul_f32_e32 v62, v56, v62
	v_add_f32_e32 v56, v57, v128
	v_sub_f32_e32 v56, v56, v69
	v_mul_f32_e32 v57, 0x3fb8aa3b, v56
	v_mul_f32_e32 v56, 0xbfb8aa3b, v56
	v_exp_f32_e32 v56, v56
	v_sub_f32_e32 v54, v54, v66
	v_lshlrev_b32_e32 v64, 16, v99
	v_sub_f32_e32 v123, v70, v66
	v_mul_f32_e32 v63, v56, v63
	v_mul_f32_e32 v56, 0x3fb8aa3b, v54
	v_mul_f32_e32 v54, 0xbfb8aa3b, v54
	v_exp_f32_e32 v54, v54
	v_exp_f32_e32 v130, v130
	v_exp_f32_e32 v57, v57
	v_exp_f32_e32 v56, v56
	v_mul_f32_e32 v64, v54, v64
	v_add_f32_e32 v54, v55, v77
	v_sub_f32_e32 v54, v54, v67
	v_mul_f32_e32 v55, 0x3fb8aa3b, v54
	v_exp_f32_e32 v55, v55
	v_mul_f32_e32 v123, 0x3fb8aa3b, v123
	v_mul_f32_e32 v54, 0xbfb8aa3b, v54
	v_exp_f32_e32 v123, v123
	v_cvt_pk_bf16_f32 v61, v132, v133
	v_exp_f32_e32 v54, v54
	ds_write2st64_b64 v108, v[58:59], v[60:61] offset1:34
	v_lshlrev_b32_e32 v58, 16, v100
	v_and_b32_e32 v59, 0xffff0000, v100
	v_lshlrev_b32_e32 v60, 16, v101
	v_and_b32_e32 v61, 0xffff0000, v101
	v_mul_f32_e32 v58, v130, v58
	v_mul_f32_e32 v57, v57, v59
	v_mul_f32_e32 v56, v56, v60
	v_mul_f32_e32 v55, v55, v61
	v_add_f32_e32 v50, v50, v129
	v_and_b32_e32 v65, 0xffff0000, v99
	v_mul_f32_e32 v130, v16, v58
	v_mul_f32_e32 v59, v75, v57
	v_mul_f32_e32 v60, v119, v56
	v_mul_f32_e32 v61, v126, v55
	v_cvt_pk_bf16_f32 v55, v56, v55
	v_cvt_pk_bf16_f32 v56, v130, v59
	v_sub_f32_e32 v50, v50, v68
	v_mul_f32_e32 v182, v123, v177
	v_mul_f32_e32 v177, v117, v131
	v_mul_f32_e32 v131, v74, v62
	v_mul_f32_e32 v65, v54, v65
	v_cvt_pk_bf16_f32 v54, v58, v57
	v_cvt_pk_bf16_f32 v57, v60, v61
	ds_write_b64 v147, v[56:57] offset:34816
	v_cvt_pk_bf16_f32 v56, v62, v63
	v_mul_f32_e32 v62, 0x3fb8aa3b, v50
	v_mul_f32_e32 v50, 0xbfb8aa3b, v50
	v_exp_f32_e32 v50, v50
	v_lshlrev_b32_e32 v58, 16, v110
	v_and_b32_e32 v59, 0xffff0000, v110
	v_lshlrev_b32_e32 v60, 16, v111
	v_mul_f32_e32 v58, v50, v58
	v_add_f32_e32 v50, v51, v128
	v_sub_f32_e32 v50, v50, v69
	v_mul_f32_e32 v51, 0x3fb8aa3b, v50
	v_mul_f32_e32 v50, 0xbfb8aa3b, v50
	v_exp_f32_e32 v50, v50
	v_exp_f32_e32 v62, v62
	v_exp_f32_e32 v51, v51
	v_sub_f32_e32 v127, v71, v67
	v_mul_f32_e32 v59, v50, v59
	v_add_f32_e32 v50, v52, v76
	v_sub_f32_e32 v50, v50, v66
	v_mul_f32_e32 v52, 0x3fb8aa3b, v50
	v_mul_f32_e32 v50, 0xbfb8aa3b, v50
	v_exp_f32_e32 v50, v50
	v_exp_f32_e32 v52, v52
	v_mul_f32_e32 v127, 0x3fb8aa3b, v127
	v_cvt_pk_bf16_f32 v57, v64, v65
	v_mul_f32_e32 v60, v50, v60
	v_add_f32_e32 v50, v53, v77
	v_sub_f32_e32 v50, v50, v67
	v_mul_f32_e32 v53, 0x3fb8aa3b, v50
	v_mul_f32_e32 v50, 0xbfb8aa3b, v50
	v_exp_f32_e32 v53, v53
	v_exp_f32_e32 v50, v50
	ds_write2st64_b64 v147, v[54:55], v[56:57] offset1:34
	v_lshlrev_b32_e32 v54, 16, v112
	v_and_b32_e32 v55, 0xffff0000, v112
	v_lshlrev_b32_e32 v56, 16, v113
	v_exp_f32_e32 v127, v127
	v_and_b32_e32 v57, 0xffff0000, v113
	v_and_b32_e32 v61, 0xffff0000, v111
	v_mul_f32_e32 v54, v62, v54
	v_mul_f32_e32 v51, v51, v55
	v_mul_f32_e32 v52, v52, v56
	v_mul_f32_e32 v16, v16, v54
	v_mul_f32_e32 v55, v75, v51
	v_mul_f32_e32 v56, v119, v52
	v_mul_f32_e32 v53, v53, v57
	v_mul_f32_e32 v61, v50, v61
	v_cvt_pk_bf16_f32 v50, v54, v51
	v_cvt_pk_bf16_f32 v51, v52, v53
	v_cvt_pk_bf16_f32 v52, v16, v55
	v_mul_f32_e32 v57, v126, v53
	v_cvt_pk_bf16_f32 v53, v56, v57
	ds_write_b64 v165, v[52:53] offset:34816
	v_cvt_pk_bf16_f32 v52, v58, v59
	v_and_b32_e32 v16, 0xffff, v82
	v_mul_f32_e32 v62, v74, v58
	v_cvt_pk_bf16_f32 v53, v60, v61
	ds_write2st64_b64 v165, v[50:51], v[52:53] offset1:34
	v_cvt_pk_bf16_f32 v50, v180, v176
	v_cvt_pk_bf16_f32 v51, v131, v62
	v_lshl_or_b32 v52, v90, 16, v16
	v_add_u32_e32 v16, 0xc800, v166
	v_mul_f32_e32 v183, v127, v178
	v_mul_f32_e32 v178, v123, v132
	v_mul_f32_e32 v132, v117, v63
	v_mul_f32_e32 v63, v117, v59
	v_and_b32_e32 v53, 0xffff, v102
	v_cvt_pk_bf16_f32 v54, v181, v177
	v_cvt_pk_bf16_f32 v55, v132, v63
	ds_write2_b64 v16, v[50:51], v[54:55] offset0:128 offset1:146
	v_lshrrev_b32_e32 v50, 16, v82
	v_lshrrev_b32_e32 v51, 16, v102
	v_lshl_or_b32 v53, v120, 16, v53
	v_and_or_b32 v50, v90, s49, v50
	v_and_or_b32 v51, v120, s49, v51
	v_mul_f32_e32 v179, v127, v133
	v_mul_f32_e32 v133, v123, v64
	v_mul_f32_e32 v64, v123, v60
	ds_write2_b64 v167, v[52:53], v[50:51] offset1:18
	v_cvt_pk_bf16_f32 v51, v133, v64
	v_mul_f32_e32 v175, v127, v65
	v_mul_f32_e32 v65, v127, v61
	v_cvt_pk_bf16_f32 v50, v182, v178
	v_and_b32_e32 v52, 0xffff, v83
	v_and_b32_e32 v53, 0xffff, v103
	v_cvt_pk_bf16_f32 v54, v183, v179
	v_cvt_pk_bf16_f32 v55, v175, v65
	ds_write2_b64 v16, v[50:51], v[54:55] offset0:164 offset1:182
	v_lshrrev_b32_e32 v16, 16, v83
	v_lshrrev_b32_e32 v51, 16, v103
	v_lshl_or_b32 v52, v91, 16, v52
	v_lshl_or_b32 v53, v121, 16, v53
	v_and_or_b32 v50, v91, s49, v16
	v_and_or_b32 v51, v121, s49, v51
	ds_write2_b64 v167, v[52:53], v[50:51] offset0:36 offset1:54
	s_mov_b64 s[52:53], exec
	v_readlane_b32 s54, v255, 12
	v_readlane_b32 s55, v255, 13
	s_and_b64 s[54:55], s[52:53], s[54:55]
	s_mov_b64 exec, s[54:55]
	s_cbranch_execz .LBB0_414
	v_mul_f32_e32 v16, 0x3fb8aa3b, v72
	v_exp_f32_e32 v50, v16
	v_mul_f32_e32 v16, 0x3fb8aa3b, v73
	v_exp_f32_e32 v51, v16
	v_mul_f32_e32 v16, 0x3fb8aa3b, v70
	v_exp_f32_e32 v52, v16
	v_mul_f32_e32 v16, 0x3fb8aa3b, v71
	v_exp_f32_e32 v53, v16
	ds_write_b128 v137, v[50:53]

; __device__ __forceinline__ unsigned cvt_pk_bf16(float lo, float hi) { unsigned r; asm("v_cvt_pk_bf16_f32 %0, %1, %2" : "=v"(r) : "v"(lo), "v"(hi)); return r; }
; template <int DK, int DV, bool SEPQ> ...
;     ...
;         for (int vt = 0; vt < NVT; ++vt) { const f32x4 s = S[ct][vt]; u32x2 w; w.x = cvt_pk_bf16(s[0], s[1]); w.y = cvt_pk_bf16(s[2], s[3]);
;             *(u32x2*)(ST + (16 * vt + fr) * LQ + 16 * (wid * NCTW + ct) + 4 * fq) = w; }
;     __syncthreads();
;     {
;         const float gi_i = GI[16 * m + fr];
;         const int n0 = 2 * hw, n1 = 2 * hw + 1; const bool do0 = n0 <= m, do1 = n1 <= m;
;         f32x4 acc0 = {0.f, 0.f, 0.f, 0.f}, acc1 = {0.f, 0.f, 0.f, 0.f};
; #pragma unroll
;         for (int vt = 0; vt < NVTW; ++vt) O[vt] = (f32x4){0.f, 0.f, 0.f, 0.f};
; #pragma unroll
;         for (int ks = 0; ks < DK / 32; ++ks) {
;             const bf16x8 qf = *(const bf16x8*)(QA + (16 * m + fr) * LQ + 32 * ks + 8 * fq);
;             if (do0) { const bf16x8 kf = *(const bf16x8*)(KB + (16 * n0 + fr) * LQ + 32 * ks + 8 * fq); acc0 = __builtin_amdgcn_mfma_f32_16x16x32_bf16(kf, qf, acc0, 0, 0, 0); }
;             if (do1) { const bf16x8 kf = *(const bf16x8*)(KB + (16 * n1 + fr) * LQ + 32 * ks + 8 * fq); acc1 = __builtin_amdgcn_mfma_f32_16x16x32_bf16(kf, qf, acc1, 0, 0, 0); }
;             bf16x8 qs = qf; if (SEPQ) qs = *(const bf16x8*)(QS + (16 * m + fr) * LQ + 32 * ks + 8 * fq);
; #pragma unroll
;             for (int vt = 0; vt < NVTW; ++vt) { const bf16x8 sf = *(const bf16x8*)(ST + (16 * (hw * NVTW + vt) + fr) * LQ + 32 * ks + 8 * fq); O[vt] = __builtin_amdgcn_mfma_f32_16x16x32_bf16(sf, qs, O[vt], 0, 0, 0); }
;         }
; #pragma unroll
;         for (int nn = 0; nn < 2; ++nn) {
;             const int n = 2 * hw + nn; const f32x4 acc = nn == 0 ? acc0 : acc1;
;             const f32x4 gj = *(const f32x4*)(GI + 16 * n + 4 * fq); const int i = 16 * m + fr, j0 = 16 * n + 4 * fq; float p[4];
; #pragma unroll
;             for (int e = 0; e < 4; ++e) p[e] = (j0 + e <= i) ? acc[e] * __expf(gi_i - gj[e]) : 0.f;
;             u32x2 w; w.x = cvt_pk_bf16(p[0], p[1]); w.y = cvt_pk_bf16(p[2], p[3]); *(u32x2*)(P + (16 * m + fr) * LJ + j0) = w;
;         }
;         const float ei = __expf(gi_i);
; #pragma unroll
;         for (int vt = 0; vt < NVTW; ++vt) O[vt] = O[vt] * ei;
;     }
.LBB0_420:
	s_lshl_b32 s54, s62, 9
	s_mov_b32 s55, s12
	v_lshl_add_u64 v[218:219], v[114:115], 0, s[54:55]
	global_load_dwordx4 v[202:205], v[218:219], off
	global_load_dwordx4 v[206:209], v[218:219], off offset:64
	global_load_dwordx4 v[210:213], v[218:219], off offset:128
	global_load_dwordx4 v[214:217], v[218:219], off offset:192
	v_cvt_pk_bf16_f32 v50, v18, v19
	v_cvt_pk_bf16_f32 v51, v20, v21
	ds_write_b64 v169, v[50:51]
	v_cvt_pk_bf16_f32 v50, v22, v23
	v_cvt_pk_bf16_f32 v51, v24, v25
	ds_write_b64 v169, v[50:51] offset:4352
	v_cvt_pk_bf16_f32 v50, v26, v27
	v_cvt_pk_bf16_f32 v51, v28, v29
	ds_write_b64 v169, v[50:51] offset:8704
	v_cvt_pk_bf16_f32 v50, v30, v31
	v_cvt_pk_bf16_f32 v51, v32, v33
	ds_write_b64 v169, v[50:51] offset:13056
	v_cvt_pk_bf16_f32 v50, v34, v35
	v_cvt_pk_bf16_f32 v51, v36, v37
	ds_write_b64 v169, v[50:51] offset:17408
	v_cvt_pk_bf16_f32 v50, v38, v39
	v_cvt_pk_bf16_f32 v51, v40, v41
	ds_write_b64 v169, v[50:51] offset:21760
	v_cvt_pk_bf16_f32 v50, v42, v43
	v_cvt_pk_bf16_f32 v51, v44, v45
	ds_write_b64 v169, v[50:51] offset:26112
	v_cvt_pk_bf16_f32 v50, v46, v47
	v_cvt_pk_bf16_f32 v51, v48, v49
	ds_write_b64 v169, v[50:51] offset:30464
	s_waitcnt lgkmcnt(0)
	s_barrier
	ds_read_b32 v16, v138
	ds_read_b128 v[218:221], v139
	ds_read_b128 v[222:225], v140 offset:17408
	ds_read_b128 v[226:229], v140 offset:21760
	ds_read_b128 v[242:245], v139 offset:34816
	ds_read_b128 v[246:249], v174
	ds_read_b128 v[74:77], v174 offset:4352
	ds_read_b128 v[176:179], v174 offset:8704
	ds_read_b128 v[180:183], v174 offset:13056
	ds_read_b128 v[230:233], v139 offset:64
	ds_read_b128 v[234:237], v140 offset:17472
	ds_read_b128 v[238:241], v140 offset:21824
	s_waitcnt lgkmcnt(8)
	v_mfma_f32_16x16x32_bf16 v[54:57], v[222:225], v[218:221], 0
	v_mfma_f32_16x16x32_bf16 v[50:53], v[226:229], v[218:221], 0
	s_waitcnt lgkmcnt(3)
	v_mfma_f32_16x16x32_bf16 v[58:61], v[246:249], v[242:245], 0
	v_mfma_f32_16x16x32_bf16 v[62:65], v[74:77], v[242:245], 0
	v_mfma_f32_16x16x32_bf16 v[66:69], v[176:179], v[242:245], 0
	v_mfma_f32_16x16x32_bf16 v[70:73], v[180:183], v[242:245], 0
	ds_read_b128 v[242:245], v139 offset:34880
	ds_read_b128 v[246:249], v174 offset:64
	ds_read_b128 v[74:77], v174 offset:4416
	ds_read_b128 v[176:179], v174 offset:8768
	ds_read_b128 v[180:183], v174 offset:13120
	ds_read_b128 v[218:221], v139 offset:128
	ds_read_b128 v[222:225], v140 offset:17536
	ds_read_b128 v[226:229], v140 offset:21888
	s_waitcnt lgkmcnt(8)
	v_mfma_f32_16x16x32_bf16 v[54:57], v[234:237], v[230:233], v[54:57]
	v_mfma_f32_16x16x32_bf16 v[50:53], v[238:241], v[230:233], v[50:53]
	s_waitcnt lgkmcnt(3)
	v_mfma_f32_16x16x32_bf16 v[58:61], v[246:249], v[242:245], v[58:61]
	v_mfma_f32_16x16x32_bf16 v[62:65], v[74:77], v[242:245], v[62:65]
	v_mfma_f32_16x16x32_bf16 v[66:69], v[176:179], v[242:245], v[66:69]
	v_mfma_f32_16x16x32_bf16 v[70:73], v[180:183], v[242:245], v[70:73]
	ds_read_b128 v[242:245], v139 offset:34944
	ds_read_b128 v[246:249], v174 offset:128
	ds_read_b128 v[74:77], v174 offset:4480
	ds_read_b128 v[176:179], v174 offset:8832
	ds_read_b128 v[180:183], v174 offset:13184
	ds_read_b128 v[230:233], v139 offset:192
	ds_read_b128 v[234:237], v140 offset:17600
	ds_read_b128 v[238:241], v140 offset:21952
	s_waitcnt lgkmcnt(8)
	v_mfma_f32_16x16x32_bf16 v[54:57], v[222:225], v[218:221], v[54:57]
	v_mfma_f32_16x16x32_bf16 v[50:53], v[226:229], v[218:221], v[50:53]
	s_waitcnt lgkmcnt(3)
	v_mfma_f32_16x16x32_bf16 v[58:61], v[246:249], v[242:245], v[58:61]
	v_mfma_f32_16x16x32_bf16 v[62:65], v[74:77], v[242:245], v[62:65]
	v_mfma_f32_16x16x32_bf16 v[66:69], v[176:179], v[242:245], v[66:69]
	v_mfma_f32_16x16x32_bf16 v[70:73], v[180:183], v[242:245], v[70:73]
	ds_read_b128 v[242:245], v139 offset:35008
	ds_read_b128 v[246:249], v174 offset:192
	ds_read_b128 v[74:77], v174 offset:4544
	ds_read_b128 v[176:179], v174 offset:8896
	ds_read_b128 v[180:183], v174 offset:13248
	s_waitcnt lgkmcnt(5)
	v_mfma_f32_16x16x32_bf16 v[54:57], v[234:237], v[230:233], v[54:57]
	v_mfma_f32_16x16x32_bf16 v[50:53], v[238:241], v[230:233], v[50:53]
	s_waitcnt lgkmcnt(0)
	v_mfma_f32_16x16x32_bf16 v[58:61], v[246:249], v[242:245], v[58:61]
	v_mfma_f32_16x16x32_bf16 v[62:65], v[74:77], v[242:245], v[62:65]
	v_mfma_f32_16x16x32_bf16 v[66:69], v[176:179], v[242:245], v[66:69]
	v_mfma_f32_16x16x32_bf16 v[70:73], v[180:183], v[242:245], v[70:73]
	s_nop 7
	v_readlane_b32 s52, v255, 14
	v_readlane_b32 s53, v255, 15
	ds_read_b128 v[74:77], v141
	s_waitcnt lgkmcnt(0)
	v_sub_f32_e32 v74, v16, v74
	v_mul_f32_e32 v74, 0x3fb8aa3b, v74
	v_exp_f32_e32 v74, v74
	s_nop 0
	v_mul_f32_e32 v54, v54, v74
	v_sub_f32_e32 v74, v16, v75
	v_mul_f32_e32 v74, 0x3fb8aa3b, v74
	v_exp_f32_e32 v74, v74
	v_cndmask_b32_e64 v54, v54, 0, s[52:53]
	v_readlane_b32 s52, v255, 16
	v_readlane_b32 s53, v255, 17
	v_mul_f32_e32 v55, v55, v74
	v_sub_f32_e32 v74, v16, v76
	v_mul_f32_e32 v74, 0x3fb8aa3b, v74
	v_exp_f32_e32 v74, v74
	v_cndmask_b32_e64 v55, 0, v55, s[52:53]
	v_readlane_b32 s52, v255, 18
	v_readlane_b32 s53, v255, 19
	v_mul_f32_e32 v56, v56, v74
	v_sub_f32_e32 v74, v16, v77
	v_mul_f32_e32 v74, 0x3fb8aa3b, v74
	v_exp_f32_e32 v74, v74
	v_cndmask_b32_e64 v56, v56, 0, s[52:53]
	v_readlane_b32 s52, v255, 20
	v_readlane_b32 s53, v255, 21
	v_mul_f32_e32 v57, v57, v74
	v_cvt_pk_bf16_f32 v54, v54, v55
	s_nop 0
	v_cndmask_b32_e64 v57, v57, 0, s[52:53]
	v_cvt_pk_bf16_f32 v55, v56, v57
	ds_write_b64 v142, v[54:55]
	ds_read_b128 v[54:57], v141 offset:64
	v_readlane_b32 s52, v255, 22
	v_readlane_b32 s53, v255, 23
	s_waitcnt lgkmcnt(0)
	v_sub_f32_e32 v54, v16, v54
	v_mul_f32_e32 v54, 0x3fb8aa3b, v54
	v_exp_f32_e32 v54, v54
	s_nop 0
	v_mul_f32_e32 v50, v50, v54
	v_sub_f32_e32 v54, v16, v55
	v_mul_f32_e32 v54, 0x3fb8aa3b, v54
	v_exp_f32_e32 v54, v54
	v_cndmask_b32_e64 v50, v50, 0, s[52:53]
	v_readlane_b32 s52, v255, 24
	v_readlane_b32 s53, v255, 25
	v_mul_f32_e32 v51, v51, v54
	v_sub_f32_e32 v54, v16, v56
	v_mul_f32_e32 v54, 0x3fb8aa3b, v54
	v_exp_f32_e32 v54, v54
	v_cndmask_b32_e64 v51, 0, v51, s[52:53]
	v_readlane_b32 s52, v255, 26
	v_readlane_b32 s53, v255, 27
	v_mul_f32_e32 v52, v52, v54
	v_sub_f32_e32 v54, v16, v57
	v_mul_f32_e32 v54, 0x3fb8aa3b, v54
	v_exp_f32_e32 v54, v54
	v_mul_f32_e32 v16, 0x3fb8aa3b, v16
	v_exp_f32_e32 v16, v16
	v_cndmask_b32_e64 v52, v52, 0, s[52:53]
	v_readlane_b32 s52, v255, 28
	v_mul_f32_e32 v53, v53, v54
	v_readlane_b32 s53, v255, 29
	v_cvt_pk_bf16_f32 v50, v50, v51
	v_pk_mul_f32 v[54:55], v[16:17], v[62:63] op_sel_hi:[0,1]
	v_pk_mul_f32 v[56:57], v[16:17], v[64:65] op_sel_hi:[0,1]
	v_cndmask_b32_e64 v53, v53, 0, s[52:53]
	v_cvt_pk_bf16_f32 v51, v52, v53
	ds_write_b64 v142, v[50:51] offset:32
	v_pk_mul_f32 v[50:51], v[16:17], v[58:59] op_sel_hi:[0,1]
	v_pk_mul_f32 v[52:53], v[16:17], v[60:61] op_sel_hi:[0,1]
	v_pk_mul_f32 v[58:59], v[16:17], v[66:67] op_sel_hi:[0,1]
	v_pk_mul_f32 v[60:61], v[16:17], v[68:69] op_sel_hi:[0,1]
	v_pk_mul_f32 v[62:63], v[16:17], v[70:71] op_sel_hi:[0,1]
	v_pk_mul_f32 v[64:65], v[16:17], v[72:73] op_sel_hi:[0,1]
	s_waitcnt lgkmcnt(0)
	s_barrier
; template <int DK, int DV, bool SEPQ> ...
;     ...
; #pragma unroll
;     for (int ks = 0; ks < 2; ++ks) { const bf16x8 pf = *(const bf16x8*)(P + (16 * m + fr) * LJ + 32 * ks + 8 * fq);
; #pragma unroll
;         for (int vt = 0; vt < NVTW; ++vt) { const bf16x8 vf = *(const bf16x8*)(VT + (16 * (hw * NVTW + vt) + fr) * LJ + 32 * ks + 8 * fq); O[vt] = __builtin_amdgcn_mfma_f32_16x16x32_bf16(vf, pf, O[vt], 0, 0, 0); } }
; #pragma unroll
;     for (int ct = 0; ct < NCTW; ++ct) { const int ctg = wid * NCTW + ct; const f32x4 dec = *(const f32x4*)(SDEC + 16 * ctg + 4 * fq);
; #pragma unroll
;         for (int vt = 0; vt < NVT; ++vt) S[ct][vt] = S[ct][vt] * dec;
; #pragma unroll
;         for (int ks = 0; ks < 2; ++ks) { const bf16x8 kf = *(const bf16x8*)(KT + (16 * ctg + fr) * LJ + 32 * ks + 8 * fq);
; #pragma unroll
;             for (int vt = 0; vt < NVT; ++vt) { const bf16x8 vf = *(const bf16x8*)(VT2 + (16 * vt + fr) * LJ + 32 * ks + 8 * fq); S[ct][vt] = __builtin_amdgcn_mfma_f32_16x16x32_bf16(kf, vf, S[ct][vt], 0, 0, 0); } } }
; __device__ __forceinline__ void hg_block(ArgsP a_, int jl, unsigned char* smem) { const ArgsP a = a_;
;     ...
;         { float ss = 0.f;
; #pragma unroll
;           for (int vt = 0; vt < 4; ++vt) ss += (O[vt][0] * O[vt][0] + O[vt][1] * O[vt][1]) + (O[vt][2] * O[vt][2] + O[vt][3] * O[vt][3]);
;           ss += __shfl_xor(ss, 16); ss += __shfl_xor(ss, 32); if (fq == 0) RSm[irow * 2 + hw] = ss; }
	ds_read_b128 v[218:221], v143
	ds_read_b128 v[222:225], v143 offset:64
	ds_read_b128 v[226:229], v170
	ds_read_b128 v[230:233], v170 offset:2304
	ds_read_b128 v[234:237], v170 offset:4608
	ds_read_b128 v[238:241], v170 offset:6912
	ds_read_b128 v[242:245], v170 offset:64
	ds_read_b128 v[246:249], v170 offset:2368
	ds_read_b128 v[74:77], v170 offset:4672
	ds_read_b128 v[176:179], v170 offset:6976
	s_waitcnt lgkmcnt(7)
	v_mfma_f32_16x16x32_bf16 v[50:53], v[226:229], v[218:221], v[50:53]
	s_waitcnt lgkmcnt(6)
	v_mfma_f32_16x16x32_bf16 v[54:57], v[230:233], v[218:221], v[54:57]
	s_waitcnt lgkmcnt(5)
	v_mfma_f32_16x16x32_bf16 v[70:73], v[234:237], v[218:221], v[58:61]
	s_waitcnt lgkmcnt(4)
	v_mfma_f32_16x16x32_bf16 v[66:69], v[238:241], v[218:221], v[62:65]
	s_waitcnt lgkmcnt(3)
	v_mfma_f32_16x16x32_bf16 v[62:65], v[242:245], v[222:225], v[50:53]
	s_waitcnt lgkmcnt(2)
	v_mfma_f32_16x16x32_bf16 v[58:61], v[246:249], v[222:225], v[54:57]
	s_waitcnt lgkmcnt(1)
	v_mfma_f32_16x16x32_bf16 v[54:57], v[74:77], v[222:225], v[70:73]
	s_waitcnt lgkmcnt(0)
	v_mfma_f32_16x16x32_bf16 v[50:53], v[176:179], v[222:225], v[66:69]
	ds_read_b128 v[180:183], v171
	ds_read_b128 v[74:77], v144 offset:52224
	ds_read_b128 v[176:179], v144 offset:52288
	ds_read_b128 v[218:221], v172
	ds_read_b128 v[222:225], v172 offset:2304
	ds_read_b128 v[226:229], v172 offset:4608
	ds_read_b128 v[230:233], v172 offset:6912
	ds_read_b128 v[234:237], v172 offset:9216
	ds_read_b128 v[238:241], v172 offset:11520
	ds_read_b128 v[242:245], v172 offset:13824
	ds_read_b128 v[246:249], v172 offset:16128
	s_waitcnt lgkmcnt(10)
	v_pk_mul_f32 v[18:19], v[18:19], v[180:181]
	v_pk_mul_f32 v[20:21], v[20:21], v[182:183]
	v_pk_mul_f32 v[22:23], v[22:23], v[180:181]
	v_pk_mul_f32 v[24:25], v[24:25], v[182:183]
	v_pk_mul_f32 v[26:27], v[26:27], v[180:181]
	v_pk_mul_f32 v[28:29], v[28:29], v[182:183]
	v_pk_mul_f32 v[30:31], v[30:31], v[180:181]
	v_pk_mul_f32 v[32:33], v[32:33], v[182:183]
	v_pk_mul_f32 v[34:35], v[34:35], v[180:181]
	v_pk_mul_f32 v[36:37], v[36:37], v[182:183]
	v_pk_mul_f32 v[38:39], v[38:39], v[180:181]
	v_pk_mul_f32 v[40:41], v[40:41], v[182:183]
	v_pk_mul_f32 v[42:43], v[42:43], v[180:181]
	v_pk_mul_f32 v[44:45], v[44:45], v[182:183]
	v_pk_mul_f32 v[46:47], v[46:47], v[180:181]
	v_pk_mul_f32 v[48:49], v[48:49], v[182:183]
	v_mul_f32_e32 v16, v63, v63
	v_fmac_f32_e32 v16, v62, v62
	ds_read_b128 v[66:69], v172 offset:64
	ds_read_b128 v[70:73], v172 offset:2368
	s_waitcnt lgkmcnt(9)
	v_mfma_f32_16x16x32_bf16 v[18:21], v[74:77], v[218:221], v[18:21]
	ds_read_b128 v[218:221], v172 offset:4672
	s_waitcnt lgkmcnt(9)
	v_mfma_f32_16x16x32_bf16 v[22:25], v[74:77], v[222:225], v[22:25]
	ds_read_b128 v[222:225], v172 offset:6976
	s_waitcnt lgkmcnt(9)
	v_mfma_f32_16x16x32_bf16 v[26:29], v[74:77], v[226:229], v[26:29]
	ds_read_b128 v[226:229], v172 offset:9280
	s_waitcnt lgkmcnt(9)
	v_mfma_f32_16x16x32_bf16 v[30:33], v[74:77], v[230:233], v[30:33]
	ds_read_b128 v[230:233], v172 offset:11584
	s_waitcnt lgkmcnt(9)
	v_mfma_f32_16x16x32_bf16 v[34:37], v[74:77], v[234:237], v[34:37]
	ds_read_b128 v[234:237], v172 offset:13888
	s_waitcnt lgkmcnt(9)
	v_mfma_f32_16x16x32_bf16 v[38:41], v[74:77], v[238:241], v[38:41]
	ds_read_b128 v[238:241], v172 offset:16192
	s_waitcnt lgkmcnt(9)
	v_mfma_f32_16x16x32_bf16 v[42:45], v[74:77], v[242:245], v[42:45]
	s_waitcnt lgkmcnt(8)
	v_mfma_f32_16x16x32_bf16 v[46:49], v[74:77], v[246:249], v[46:49]
	s_waitcnt lgkmcnt(7)
	v_mfma_f32_16x16x32_bf16 v[18:21], v[176:179], v[66:69], v[18:21]
	s_waitcnt lgkmcnt(6)
	v_mfma_f32_16x16x32_bf16 v[22:25], v[176:179], v[70:73], v[22:25]
	s_waitcnt lgkmcnt(5)
	v_mfma_f32_16x16x32_bf16 v[26:29], v[176:179], v[218:221], v[26:29]
	s_waitcnt lgkmcnt(4)
	v_mfma_f32_16x16x32_bf16 v[30:33], v[176:179], v[222:225], v[30:33]
	s_waitcnt lgkmcnt(3)
	v_mfma_f32_16x16x32_bf16 v[34:37], v[176:179], v[226:229], v[34:37]
	s_waitcnt lgkmcnt(2)
	v_mfma_f32_16x16x32_bf16 v[38:41], v[176:179], v[230:233], v[38:41]
	s_waitcnt lgkmcnt(1)
	v_mfma_f32_16x16x32_bf16 v[42:45], v[176:179], v[234:237], v[42:45]
	s_waitcnt lgkmcnt(0)
	v_mfma_f32_16x16x32_bf16 v[46:49], v[176:179], v[238:241], v[46:49]
	s_nop 7
	v_mul_f32_e32 v66, v65, v65
	v_fmac_f32_e32 v66, v64, v64
	v_add_f32_e32 v16, v16, v66
	v_mul_f32_e32 v66, v59, v59
	v_mul_f32_e32 v67, v61, v61
	v_fmac_f32_e32 v66, v58, v58
	v_fmac_f32_e32 v67, v60, v60
	v_add_f32_e32 v66, v66, v67
	v_add_f32_e32 v16, v16, v66
	v_mul_f32_e32 v66, v55, v55
	v_mul_f32_e32 v67, v57, v57
	v_fmac_f32_e32 v66, v54, v54
	v_fmac_f32_e32 v67, v56, v56
	v_add_f32_e32 v66, v66, v67
	v_add_f32_e32 v16, v16, v66
	v_mul_f32_e32 v66, v51, v51
	v_mul_f32_e32 v67, v53, v53
	v_fmac_f32_e32 v66, v50, v50
	v_fmac_f32_e32 v67, v52, v52
	v_add_f32_e32 v66, v66, v67
	v_and_b32_e32 v67, 64, v188
	v_add_f32_e32 v16, v16, v66
	v_xor_b32_e32 v66, 16, v188
	v_add_u32_e32 v67, 64, v67
	v_cmp_lt_i32_e32 vcc, v66, v67
	s_nop 1
	v_cndmask_b32_e32 v66, v188, v66, vcc
	v_lshlrev_b32_e32 v66, 2, v66
	ds_bpermute_b32 v66, v66, v16
	s_waitcnt lgkmcnt(0)
	v_add_f32_e32 v16, v16, v66
	v_xor_b32_e32 v66, 32, v188
	v_cmp_lt_i32_e32 vcc, v66, v67
	s_nop 1
	v_cndmask_b32_e32 v66, v188, v66, vcc
	v_lshlrev_b32_e32 v66, 2, v66
	ds_bpermute_b32 v66, v66, v16
	s_mov_b64 s[52:53], exec
	v_readlane_b32 s54, v255, 30
	v_readlane_b32 s55, v255, 31
	s_and_b64 s[54:55], s[52:53], s[54:55]
	s_mov_b64 exec, s[54:55]
	s_cbranch_execz .LBB0_438
	s_waitcnt lgkmcnt(0)
	v_add_f32_e32 v16, v16, v66
	ds_write_b32 v173, v16
